# attn stagger + removed 5 full vmcnt(0) drains at GEMM tile boundaries
# speedup vs baseline: 1.0034x; 1.0034x over previous
; DI float fast_exp2(float x) { return __builtin_amdgcn_exp2f(x); }
; DI float fast_rcp(float x) { return __builtin_amdgcn_rcpf(x); }
;     DI void operator()(Acc& acc, const pg8::Unit& u, int wr, int wc, int fr, int fq, const Pre& pr) const {
;         const int col = u.pn * 128 + wc * 32 + fq * 8;
; #pragma unroll
;         for (int ai = 0; ai < 2; ++ai)
; #pragma unroll
;             for (int m = 0; m < 4; ++m) {
;                 const int row = u.pm * 256 + ai * 128 + wr * 64 + m * 16 + fr;
;                 const float msq = msq_of(pr.v[ai * 4 + m]), nrl = -1.4426950408889634f * __builtin_amdgcn_rsqf(msq);
;                 f32x4 h[2];
; #pragma unroll
;                 for (int n = 0; n < 2; ++n)
; #pragma unroll
;                     for (int i = 0; i < 4; ++i) { const float ga = acc[ai][0][m][n][i], ua = acc[ai][1][m][n][i];
;                         const float e = fast_exp2(ga * nrl); h[n][i] = (ga * ua) * fast_rcp(__builtin_fmaf(e, msq, msq)); }
;                 store8(H + (size_t)row * FF + col, h[0], h[1]);
;             }
;     }
.LBB0_182:
	v_fmamk_f32 v170, v166, 0x3a800000, v161
	v_rsq_f32_e32 v166, v170
	v_pk_mul_f32 v[122:123], v[126:127], v[122:123]
	v_pk_mul_f32 v[124:125], v[128:129], v[124:125]
	v_pk_mul_f32 v[114:115], v[118:119], v[114:115]
	v_mul_f32_e32 v171, 0xbfb8aa3b, v166
	v_mul_f32_e32 v166, v171, v126
	v_mul_f32_e32 v167, v171, v127
	v_mul_f32_e32 v126, v171, v128
	v_mul_f32_e32 v127, v171, v129
	v_exp_f32_e32 v126, v126
	v_exp_f32_e32 v127, v127
	v_mul_f32_e32 v128, v171, v118
	v_mul_f32_e32 v129, v171, v119
	v_fma_f32 v126, v126, v170, v170
	v_fma_f32 v127, v127, v170, v170
	v_rcp_f32_e32 v126, v126
	v_rcp_f32_e32 v127, v127
	v_exp_f32_e32 v128, v128
	v_exp_f32_e32 v129, v129
	v_exp_f32_e32 v168, v166
	v_pk_mul_f32 v[124:125], v[126:127], v[124:125]
	v_fma_f32 v126, v128, v170, v170
	v_fma_f32 v127, v129, v170, v170
	v_mul_f32_e32 v128, v171, v120
	v_mul_f32_e32 v129, v171, v121
	v_exp_f32_e32 v169, v167
	v_exp_f32_e32 v128, v128
	v_exp_f32_e32 v129, v129
	v_fma_f32 v168, v168, v170, v170
	v_fma_f32 v169, v169, v170, v170
	v_rcp_f32_e32 v126, v126
	v_rcp_f32_e32 v127, v127
	v_fma_f32 v128, v128, v170, v170
	v_fmac_f32_e32 v170, v129, v170
	v_rcp_f32_e32 v168, v168
	v_rcp_f32_e32 v169, v169
	v_rcp_f32_e32 v128, v128
	v_rcp_f32_e32 v129, v170
	v_lshl_or_b32 v166, s60, 7, v159
	v_ashrrev_i32_e32 v167, 31, v166
	v_pk_mul_f32 v[116:117], v[120:121], v[116:117]
	v_pk_mul_f32 v[120:121], v[126:127], v[114:115]
	v_mov_b64_e32 v[114:115], s[10:11]
	v_pk_mul_f32 v[122:123], v[168:169], v[122:123]
	v_pk_mul_f32 v[126:127], v[128:129], v[116:117]
	v_mad_i64_i32 v[118:119], s[40:41], v156, s59, v[114:115]
	v_lshlrev_b64 v[116:117], 1, v[166:167]
	v_lshl_add_u64 v[128:129], v[118:119], 0, v[116:117]
	v_cvt_pk_bf16_f32 v118, v122, v123
	v_fmamk_f32 v122, v165, 0x3a800000, v161
	v_rsq_f32_e32 v123, v122
	v_cvt_pk_bf16_f32 v119, v124, v125
	v_pk_mul_f32 v[106:107], v[110:111], v[106:107]
	v_pk_mul_f32 v[108:109], v[112:113], v[108:109]
	v_mul_f32_e32 v123, 0xbfb8aa3b, v123
	v_mul_f32_e32 v124, v123, v110
	v_mul_f32_e32 v125, v123, v111
	v_mul_f32_e32 v110, v123, v112
	v_mul_f32_e32 v111, v123, v113
	v_exp_f32_e32 v110, v110
	v_exp_f32_e32 v111, v111
	v_mul_f32_e32 v112, v123, v102
	v_mul_f32_e32 v113, v123, v103
	v_fma_f32 v110, v110, v122, v122
	v_fma_f32 v111, v111, v122, v122
	v_rcp_f32_e32 v110, v110
	v_rcp_f32_e32 v111, v111
	v_exp_f32_e32 v112, v112
	v_exp_f32_e32 v113, v113
	v_exp_f32_e32 v124, v124
	v_exp_f32_e32 v125, v125
	v_cvt_pk_bf16_f32 v120, v120, v121
	v_cvt_pk_bf16_f32 v121, v126, v127
	v_pk_mul_f32 v[108:109], v[110:111], v[108:109]
	v_fma_f32 v110, v112, v122, v122
	v_fma_f32 v111, v113, v122, v122
	global_store_dwordx4 v[128:129], v[118:121], off
	v_rcp_f32_e32 v110, v110
	v_rcp_f32_e32 v111, v111
	v_fma_f32 v118, v124, v122, v122
	v_fma_f32 v119, v125, v122, v122
	v_rcp_f32_e32 v118, v118
	v_rcp_f32_e32 v119, v119
	v_mul_f32_e32 v112, v123, v104
	v_mul_f32_e32 v113, v123, v105
	v_exp_f32_e32 v112, v112
	v_exp_f32_e32 v113, v113
	v_pk_mul_f32 v[98:99], v[102:103], v[98:99]
	v_pk_mul_f32 v[106:107], v[118:119], v[106:107]
	v_pk_mul_f32 v[102:103], v[110:111], v[98:99]
	v_or_b32_e32 v98, 16, v156
	v_mad_i64_i32 v[98:99], s[40:41], v98, s59, v[114:115]
	v_fma_f32 v112, v112, v122, v122
	v_fmac_f32_e32 v122, v113, v122
	v_lshl_add_u64 v[110:111], v[98:99], 0, v[116:117]
	v_cvt_pk_bf16_f32 v98, v106, v107
	v_fmamk_f32 v106, v164, 0x3a800000, v161
	v_rcp_f32_e32 v112, v112
	v_rcp_f32_e32 v113, v122
	v_rsq_f32_e32 v107, v106
	v_pk_mul_f32 v[100:101], v[104:105], v[100:101]
	v_pk_mul_f32 v[90:91], v[94:95], v[90:91]
	v_pk_mul_f32 v[104:105], v[112:113], v[100:101]
	v_cvt_pk_bf16_f32 v100, v102, v103
	v_mul_f32_e32 v102, 0xbfb8aa3b, v107
	v_cvt_pk_bf16_f32 v101, v104, v105
	v_mul_f32_e32 v103, v102, v94
	v_mul_f32_e32 v104, v102, v95
	v_mul_f32_e32 v94, v102, v96
	v_mul_f32_e32 v95, v102, v97
	v_exp_f32_e32 v94, v94
	v_exp_f32_e32 v95, v95
	v_pk_mul_f32 v[92:93], v[96:97], v[92:93]
	v_mul_f32_e32 v96, v102, v86
	v_fma_f32 v94, v94, v106, v106
	v_fma_f32 v95, v95, v106, v106
	v_mul_f32_e32 v97, v102, v87
	v_rcp_f32_e32 v94, v94
	v_rcp_f32_e32 v95, v95
	v_exp_f32_e32 v96, v96
	v_exp_f32_e32 v97, v97
	v_exp_f32_e32 v103, v103
	v_exp_f32_e32 v104, v104
	v_cvt_pk_bf16_f32 v99, v108, v109
	v_pk_mul_f32 v[92:93], v[94:95], v[92:93]
	v_fma_f32 v94, v96, v106, v106
	v_fma_f32 v95, v97, v106, v106
	global_store_dwordx4 v[110:111], v[98:101], off
	v_rcp_f32_e32 v94, v94
	v_rcp_f32_e32 v95, v95
	v_fma_f32 v98, v103, v106, v106
	v_fma_f32 v99, v104, v106, v106
	v_rcp_f32_e32 v98, v98
	v_rcp_f32_e32 v99, v99
	v_mul_f32_e32 v96, v102, v88
	v_mul_f32_e32 v97, v102, v89
	v_exp_f32_e32 v96, v96
	v_exp_f32_e32 v97, v97
	v_pk_mul_f32 v[82:83], v[86:87], v[82:83]
	v_pk_mul_f32 v[90:91], v[98:99], v[90:91]
	v_pk_mul_f32 v[86:87], v[94:95], v[82:83]
	v_or_b32_e32 v82, 32, v156
	v_mad_i64_i32 v[82:83], s[40:41], v82, s59, v[114:115]
	v_fma_f32 v96, v96, v106, v106
	v_fmac_f32_e32 v106, v97, v106
	v_lshl_add_u64 v[94:95], v[82:83], 0, v[116:117]
	v_cvt_pk_bf16_f32 v82, v90, v91
	v_fmamk_f32 v90, v157, 0x3a800000, v161
	v_rcp_f32_e32 v96, v96
	v_rcp_f32_e32 v97, v106
	v_rsq_f32_e32 v91, v90
	v_pk_mul_f32 v[84:85], v[88:89], v[84:85]
	v_pk_mul_f32 v[74:75], v[78:79], v[74:75]
	v_pk_mul_f32 v[88:89], v[96:97], v[84:85]
	v_cvt_pk_bf16_f32 v84, v86, v87
	v_mul_f32_e32 v86, 0xbfb8aa3b, v91
	v_cvt_pk_bf16_f32 v85, v88, v89
	v_mul_f32_e32 v87, v86, v78
	v_mul_f32_e32 v88, v86, v79
	v_mul_f32_e32 v78, v86, v80
	v_mul_f32_e32 v79, v86, v81
	v_exp_f32_e32 v78, v78
	v_exp_f32_e32 v79, v79
	v_pk_mul_f32 v[76:77], v[80:81], v[76:77]
	v_mul_f32_e32 v80, v86, v70
	v_fma_f32 v78, v78, v90, v90
; DI float fast_exp2(float x) { return __builtin_amdgcn_exp2f(x); }
; DI float fast_rcp(float x) { return __builtin_amdgcn_rcpf(x); }
;     DI void operator()(Acc& acc, const pg8::Unit& u, int wr, int wc, int fr, int fq, const Pre& pr) const {
;     ...
;                 const float msq = msq_of(pr.v[ai * 4 + m]), nrl = -1.4426950408889634f * __builtin_amdgcn_rsqf(msq);
;                 f32x4 h[2];
; #pragma unroll
;                 for (int n = 0; n < 2; ++n)
; #pragma unroll
;                     for (int i = 0; i < 4; ++i) { const float ga = acc[ai][0][m][n][i], ua = acc[ai][1][m][n][i];
;                         const float e = fast_exp2(ga * nrl); h[n][i] = (ga * ua) * fast_rcp(__builtin_fmaf(e, msq, msq)); }
;                 store8(H + (size_t)row * FF + col, h[0], h[1]);
	v_fma_f32 v79, v79, v90, v90
	v_mul_f32_e32 v81, v86, v71
	v_rcp_f32_e32 v78, v78
	v_rcp_f32_e32 v79, v79
	v_exp_f32_e32 v80, v80
	v_exp_f32_e32 v81, v81
	v_exp_f32_e32 v87, v87
	v_exp_f32_e32 v88, v88
	v_cvt_pk_bf16_f32 v83, v92, v93
	v_pk_mul_f32 v[76:77], v[78:79], v[76:77]
	v_fma_f32 v78, v80, v90, v90
	v_fma_f32 v79, v81, v90, v90
	global_store_dwordx4 v[94:95], v[82:85], off
	v_rcp_f32_e32 v78, v78
	v_rcp_f32_e32 v79, v79
	v_fma_f32 v82, v87, v90, v90
	v_fma_f32 v83, v88, v90, v90
	v_rcp_f32_e32 v82, v82
	v_rcp_f32_e32 v83, v83
	v_mul_f32_e32 v80, v86, v72
	v_mul_f32_e32 v81, v86, v73
	v_exp_f32_e32 v80, v80
	v_exp_f32_e32 v81, v81
	v_pk_mul_f32 v[66:67], v[70:71], v[66:67]
	v_pk_mul_f32 v[74:75], v[82:83], v[74:75]
	v_pk_mul_f32 v[70:71], v[78:79], v[66:67]
	v_or_b32_e32 v66, 48, v156
	v_mad_i64_i32 v[66:67], s[40:41], v66, s59, v[114:115]
	v_fma_f32 v80, v80, v90, v90
	v_fmac_f32_e32 v90, v81, v90
	v_lshl_add_u64 v[78:79], v[66:67], 0, v[116:117]
	v_cvt_pk_bf16_f32 v66, v74, v75
	v_fmamk_f32 v74, v155, 0x3a800000, v161
	v_rcp_f32_e32 v80, v80
	v_rcp_f32_e32 v81, v90
	v_rsq_f32_e32 v75, v74
	v_pk_mul_f32 v[68:69], v[72:73], v[68:69]
	v_pk_mul_f32 v[58:59], v[62:63], v[58:59]
	v_pk_mul_f32 v[72:73], v[80:81], v[68:69]
	v_cvt_pk_bf16_f32 v68, v70, v71
	v_mul_f32_e32 v70, 0xbfb8aa3b, v75
	v_cvt_pk_bf16_f32 v69, v72, v73
	v_mul_f32_e32 v71, v70, v62
	v_mul_f32_e32 v72, v70, v63
	v_mul_f32_e32 v62, v70, v64
	v_mul_f32_e32 v63, v70, v65
	v_exp_f32_e32 v62, v62
	v_exp_f32_e32 v63, v63
	v_pk_mul_f32 v[60:61], v[64:65], v[60:61]
	v_mul_f32_e32 v64, v70, v54
	v_fma_f32 v62, v62, v74, v74
	v_fma_f32 v63, v63, v74, v74
	v_mul_f32_e32 v65, v70, v55
	v_exp_f32_e32 v71, v71
	v_exp_f32_e32 v72, v72
	v_rcp_f32_e32 v62, v62
	v_rcp_f32_e32 v63, v63
	v_exp_f32_e32 v64, v64
	v_exp_f32_e32 v65, v65
	v_cvt_pk_bf16_f32 v67, v76, v77
	global_store_dwordx4 v[78:79], v[66:69], off
	v_pk_mul_f32 v[60:61], v[62:63], v[60:61]
	v_fma_f32 v62, v64, v74, v74
	v_fma_f32 v66, v71, v74, v74
	v_fma_f32 v67, v72, v74, v74
	v_fma_f32 v63, v65, v74, v74
	v_rcp_f32_e32 v66, v66
	v_rcp_f32_e32 v67, v67
	v_rcp_f32_e32 v62, v62
	v_mul_f32_e32 v64, v70, v56
	v_mul_f32_e32 v65, v70, v57
	v_rcp_f32_e32 v63, v63
	v_exp_f32_e32 v64, v64
	v_exp_f32_e32 v65, v65
	v_pk_mul_f32 v[50:51], v[54:55], v[50:51]
	v_pk_mul_f32 v[58:59], v[66:67], v[58:59]
	v_pk_mul_f32 v[54:55], v[62:63], v[50:51]
	v_mad_i64_i32 v[50:51], s[40:41], v154, s59, v[114:115]
	v_fma_f32 v64, v64, v74, v74
	v_fmac_f32_e32 v74, v65, v74
	v_lshl_add_u64 v[62:63], v[50:51], 0, v[116:117]
	v_cvt_pk_bf16_f32 v50, v58, v59
	v_fmamk_f32 v58, v153, 0x3a800000, v161
	v_rcp_f32_e32 v64, v64
	v_rcp_f32_e32 v65, v74
	v_rsq_f32_e32 v59, v58
	v_pk_mul_f32 v[52:53], v[56:57], v[52:53]
	v_pk_mul_f32 v[42:43], v[46:47], v[42:43]
	v_pk_mul_f32 v[56:57], v[64:65], v[52:53]
	v_cvt_pk_bf16_f32 v52, v54, v55
	v_mul_f32_e32 v54, 0xbfb8aa3b, v59
	v_cvt_pk_bf16_f32 v53, v56, v57
	v_mul_f32_e32 v55, v54, v46
	v_mul_f32_e32 v56, v54, v47
	v_mul_f32_e32 v46, v54, v48
	v_mul_f32_e32 v47, v54, v49
	v_exp_f32_e32 v46, v46
	v_exp_f32_e32 v47, v47
	v_pk_mul_f32 v[44:45], v[48:49], v[44:45]
	v_mul_f32_e32 v48, v54, v38
	v_fma_f32 v46, v46, v58, v58
	v_fma_f32 v47, v47, v58, v58
	v_mul_f32_e32 v49, v54, v39
	v_exp_f32_e32 v55, v55
	v_exp_f32_e32 v56, v56
	v_rcp_f32_e32 v46, v46
	v_rcp_f32_e32 v47, v47
	v_exp_f32_e32 v48, v48
	v_exp_f32_e32 v49, v49
	v_cvt_pk_bf16_f32 v51, v60, v61
	global_store_dwordx4 v[62:63], v[50:53], off
	v_pk_mul_f32 v[44:45], v[46:47], v[44:45]
	v_fma_f32 v46, v48, v58, v58
	v_fma_f32 v50, v55, v58, v58
	v_fma_f32 v51, v56, v58, v58
	v_fma_f32 v47, v49, v58, v58
	v_rcp_f32_e32 v50, v50
	v_rcp_f32_e32 v51, v51
	v_rcp_f32_e32 v46, v46
	v_mul_f32_e32 v48, v54, v40
	v_mul_f32_e32 v49, v54, v41
	v_rcp_f32_e32 v47, v47
	v_exp_f32_e32 v48, v48
	v_exp_f32_e32 v49, v49
	v_pk_mul_f32 v[34:35], v[38:39], v[34:35]
; DI float fast_exp2(float x) { return __builtin_amdgcn_exp2f(x); }
; DI float fast_rcp(float x) { return __builtin_amdgcn_rcpf(x); }
; #define PG8_BAR __builtin_amdgcn_s_barrier()
; template <class Epi, class Sched>
; DI void gemm_phase(LAS unsigned char* lds, const Gemm g, const Sched& S, const Epi& E) {
;     ...
;         if (!has_next) break;
;         if (!(Epi::CHAIN && cur.src == 0)) {
; #pragma unroll
;             for (int a = 0; a < 2; ++a)
; #pragma unroll
;                 for (int b = 0; b < 2; ++b)
; #pragma unroll
;                     for (int m = 0; m < 4; ++m)
; #pragma unroll
;                         for (int n = 0; n < 2; ++n) acc[a][b][m][n] = (f32x4){0.f, 0.f, 0.f, 0.f};
;         }
;         cur = nxt; cA = nA; cB = nB; ++ui;
;         if (wr == 1) PG8_BAR;
;     DI void operator()(Acc& acc, const pg8::Unit& u, int wr, int wc, int fr, int fq, const Pre& pr) const {
;     ...
;                 const float msq = msq_of(pr.v[ai * 4 + m]), nrl = -1.4426950408889634f * __builtin_amdgcn_rsqf(msq);
;                 f32x4 h[2];
; #pragma unroll
;                 for (int n = 0; n < 2; ++n)
; #pragma unroll
;                     for (int i = 0; i < 4; ++i) { const float ga = acc[ai][0][m][n][i], ua = acc[ai][1][m][n][i];
;                         const float e = fast_exp2(ga * nrl); h[n][i] = (ga * ua) * fast_rcp(__builtin_fmaf(e, msq, msq)); }
;                 store8(H + (size_t)row * FF + col, h[0], h[1]);
	v_pk_mul_f32 v[42:43], v[50:51], v[42:43]
	v_pk_mul_f32 v[38:39], v[46:47], v[34:35]
	v_mad_i64_i32 v[34:35], s[40:41], v152, s59, v[114:115]
	v_fma_f32 v48, v48, v58, v58
	v_fmac_f32_e32 v58, v49, v58
	v_lshl_add_u64 v[46:47], v[34:35], 0, v[116:117]
	v_cvt_pk_bf16_f32 v34, v42, v43
	v_fmamk_f32 v42, v151, 0x3a800000, v161
	v_rcp_f32_e32 v48, v48
	v_rcp_f32_e32 v49, v58
	v_rsq_f32_e32 v43, v42
	v_pk_mul_f32 v[36:37], v[40:41], v[36:37]
	v_pk_mul_f32 v[26:27], v[30:31], v[26:27]
	v_pk_mul_f32 v[40:41], v[48:49], v[36:37]
	v_cvt_pk_bf16_f32 v36, v38, v39
	v_mul_f32_e32 v38, 0xbfb8aa3b, v43
	v_cvt_pk_bf16_f32 v37, v40, v41
	v_mul_f32_e32 v39, v38, v30
	v_mul_f32_e32 v40, v38, v31
	v_mul_f32_e32 v30, v38, v32
	v_mul_f32_e32 v31, v38, v33
	v_exp_f32_e32 v30, v30
	v_exp_f32_e32 v31, v31
	v_pk_mul_f32 v[28:29], v[32:33], v[28:29]
	v_mul_f32_e32 v32, v38, v22
	v_fma_f32 v30, v30, v42, v42
	v_fma_f32 v31, v31, v42, v42
	v_mul_f32_e32 v33, v38, v23
	v_exp_f32_e32 v39, v39
	v_exp_f32_e32 v40, v40
	v_rcp_f32_e32 v30, v30
	v_rcp_f32_e32 v31, v31
	v_exp_f32_e32 v32, v32
	v_exp_f32_e32 v33, v33
	v_cvt_pk_bf16_f32 v35, v44, v45
	global_store_dwordx4 v[46:47], v[34:37], off
	v_pk_mul_f32 v[28:29], v[30:31], v[28:29]
	v_fma_f32 v30, v32, v42, v42
	v_fma_f32 v34, v39, v42, v42
	v_fma_f32 v35, v40, v42, v42
	v_fma_f32 v31, v33, v42, v42
	v_rcp_f32_e32 v34, v34
	v_rcp_f32_e32 v35, v35
	v_rcp_f32_e32 v30, v30
	v_mul_f32_e32 v32, v38, v24
	v_mul_f32_e32 v33, v38, v25
	v_rcp_f32_e32 v31, v31
	v_exp_f32_e32 v32, v32
	v_exp_f32_e32 v33, v33
	v_pk_mul_f32 v[18:19], v[22:23], v[18:19]
	v_pk_mul_f32 v[26:27], v[34:35], v[26:27]
	v_pk_mul_f32 v[22:23], v[30:31], v[18:19]
	v_mad_i64_i32 v[18:19], s[40:41], v150, s59, v[114:115]
	v_fma_f32 v32, v32, v42, v42
	v_fmac_f32_e32 v42, v33, v42
	v_lshl_add_u64 v[30:31], v[18:19], 0, v[116:117]
	v_cvt_pk_bf16_f32 v18, v26, v27
	v_fmamk_f32 v26, v149, 0x3a800000, v161
	v_rcp_f32_e32 v32, v32
	v_rcp_f32_e32 v33, v42
	v_rsq_f32_e32 v27, v26
	v_pk_mul_f32 v[20:21], v[24:25], v[20:21]
	v_pk_mul_f32 v[10:11], v[14:15], v[10:11]
	v_pk_mul_f32 v[24:25], v[32:33], v[20:21]
	v_cvt_pk_bf16_f32 v20, v22, v23
	v_mul_f32_e32 v22, 0xbfb8aa3b, v27
	v_cvt_pk_bf16_f32 v21, v24, v25
	v_mul_f32_e32 v23, v22, v14
	v_mul_f32_e32 v24, v22, v15
	v_mul_f32_e32 v14, v22, v16
	v_mul_f32_e32 v15, v22, v17
	v_exp_f32_e32 v14, v14
	v_exp_f32_e32 v15, v15
	v_pk_mul_f32 v[12:13], v[16:17], v[12:13]
	v_mul_f32_e32 v16, v22, v6
	v_fma_f32 v14, v14, v26, v26
	v_fma_f32 v15, v15, v26, v26
	v_mul_f32_e32 v17, v22, v7
	v_rcp_f32_e32 v14, v14
	v_rcp_f32_e32 v15, v15
	v_exp_f32_e32 v16, v16
	v_exp_f32_e32 v17, v17
	v_exp_f32_e32 v23, v23
	v_pk_mul_f32 v[12:13], v[14:15], v[12:13]
	v_fma_f32 v14, v16, v26, v26
	v_fma_f32 v15, v17, v26, v26
	v_mul_f32_e32 v16, v22, v8
	v_mul_f32_e32 v17, v22, v9
	v_exp_f32_e32 v24, v24
	v_exp_f32_e32 v16, v16
	v_exp_f32_e32 v17, v17
	v_cvt_pk_bf16_f32 v19, v28, v29
	global_store_dwordx4 v[30:31], v[18:21], off
	v_fma_f32 v16, v16, v26, v26
	v_rcp_f32_e32 v14, v14
	v_fma_f32 v18, v23, v26, v26
	v_fma_f32 v19, v24, v26, v26
	v_fmac_f32_e32 v26, v17, v26
	v_rcp_f32_e32 v18, v18
	v_rcp_f32_e32 v19, v19
	v_rcp_f32_e32 v15, v15
	v_rcp_f32_e32 v16, v16
	v_rcp_f32_e32 v17, v26
	v_pk_mul_f32 v[4:5], v[8:9], v[4:5]
	v_pk_mul_f32 v[2:3], v[6:7], v[2:3]
	v_pk_mul_f32 v[10:11], v[18:19], v[10:11]
	v_pk_mul_f32 v[6:7], v[14:15], v[2:3]
	v_pk_mul_f32 v[8:9], v[16:17], v[4:5]
	v_mad_i64_i32 v[2:3], s[40:41], v148, s59, v[114:115]
	v_lshl_add_u64 v[14:15], v[2:3], 0, v[116:117]
	v_cvt_pk_bf16_f32 v2, v10, v11
	v_cvt_pk_bf16_f32 v3, v12, v13
	v_cvt_pk_bf16_f32 v4, v6, v7
	v_cvt_pk_bf16_f32 v5, v8, v9
	s_andn2_b64 vcc, exec, s[4:5]
	s_mov_b64 s[4:5], -1
	global_store_dwordx4 v[14:15], v[2:5], off
	s_cbranch_vccnz .LBB0_175
	s_andn2_b64 vcc, exec, s[8:9]
	s_cbranch_vccnz .LBB0_174
	s_barrier
	s_branch .LBB0_174

;     DI bool next(int i, Unit& u) const { if (i > 0 || c >= 64) return false; u.pm = c & 31; u.pn = 0; u.src = c >> 5; return true; }
; #define PG8_STAGE(bufoff, gbase, voff) do { _Pragma("unroll") for (int _i = 0; _i < 2; ++_i) \
;         __builtin_amdgcn_global_load_lds((const unsigned*)((const char*)(gbase) + (voff)[_i]), (LAS unsigned*)(lds + (bufoff) + ldsw + _i * 8192), 16, 0, 0); } while (0)
; #define PG8_LDA(dst, b, h) do { _Pragma("unroll") for (int m = 0; m < 4; ++m) _Pragma("unroll") for (int k = 0; k < 2; ++k) dst[m][k] = *(const LAS bf16x8*)(lds + PG8_SA(b, h) + aoff + m * 2048 + k * 1024); } while (0)
; #define PG8_LDB(dst, b, h) do { _Pragma("unroll") for (int n = 0; n < 2; ++n) _Pragma("unroll") for (int k = 0; k < 2; ++k) dst[n][k] = *(const LAS bf16x8*)(lds + PG8_SB(b, h) + boff + n * 2048 + k * 1024); } while (0)
; #define PG8_WAIT_V(n) asm volatile("s_waitcnt vmcnt(" #n ")" ::: "memory")
; #define PG8_WAIT_L(n) asm volatile("s_waitcnt lgkmcnt(" #n ")" ::: "memory")
; #define PG8_BAR __builtin_amdgcn_s_barrier()
; #define PG8_SCHED __builtin_amdgcn_sched_barrier(0)
; template <class Epi, class Sched>
; DI void gemm_phase(LAS unsigned char* lds, const Gemm g, const Sched& S, const Epi& E) {
;     ...
;         const bool has_next = S.next(ui + 1, nxt);
;         E.pre(pre, cur, wr, fr);
;         const char* nA = has_next ? (const char*)(nxt.src ? g.A1 : g.A0) + (size_t)nxt.pm * tstepA : cA; const char* nB = has_next ? (const char*)(nxt.src ? g.B1 : g.B0) + (size_t)nxt.pn * tstepB : cB;
;         for (int t = 0; t < nt; t += 2) {
;             const bool last = (t == nt - 2);
;             const char* a1 = cA + (size_t)(t + 1) * kstep;
;             const char* a2 = last ? nA : cA + (size_t)(t + 2) * kstep; const char* b2 = last ? nB : cB + (size_t)(t + 2) * kstep;
;             const char* a3 = a2 + kstep; const char* b3 = b2 + kstep;
;             PG8_LDB(B0, 0, 0); PG8_LDB(B1, 0, 1); PG8_SCHED; PG8_LDA(At, 0, 0); PG8_STAGE(PG8_SA(1, 1), a1 + hstepA, voffA);
;             PG8_WAIT_V(8); PG8_WAIT_L(0); PG8_BAR; PG8_MMA(0, 0, At, B0); PG8_MMA(0, 1, At, B1); PG8_BAR; PG8_SCHED;
;             PG8_LDA(At, 0, 1); PG8_STAGE(PG8_SB(0, 0), b2, voffB); PG8_STAGE(PG8_SB(0, 1), b2 + hstepB, voffB); PG8_STAGE(PG8_SA(0, 0), a2, voffA);
;             PG8_WAIT_V(8); PG8_WAIT_L(0); PG8_BAR; PG8_MMA(1, 0, At, B0); PG8_MMA(1, 1, At, B1); PG8_BAR; PG8_SCHED;
.LBB0_971:
	s_ashr_i32 s39, s38, 31
	s_and_b32 s67, s66, 1
	s_lshl_b64 s[40:41], s[38:39], 18
	s_cmp_eq_u32 s67, 0
	s_cselect_b32 s39, s28, s57
	s_cselect_b32 s37, s29, s58
	s_cselect_b32 s48, s50, s59
	s_cselect_b32 s49, s51, s60
	s_add_u32 s40, s39, s40
	s_addc_u32 s41, s37, s41
	s_and_b64 s[42:43], s[4:5], exec
	s_cselect_b32 s39, s41, s45
	s_cselect_b32 s68, s40, s44
	s_ashr_i32 s37, s36, 31
	s_lshl_b64 s[42:43], s[36:37], 18
	s_add_u32 s42, s48, s42
	s_addc_u32 s43, s49, s43
	s_and_b64 s[48:49], s[4:5], exec
	s_cselect_b32 s37, s43, s47
	s_cselect_b32 s69, s42, s46
	s_add_u32 s44, s44, 0x20080
	s_addc_u32 s45, s45, 0
	s_add_u32 s70, s46, 0x100
	s_addc_u32 s71, s47, 0
	s_mov_b32 s72, -2
.LBB0_972:
	v_add_u32_e32 v158, s64, v162
	v_add_u32_e32 v180, s65, v162
	ds_read_b128 v[146:149], v158
	ds_read_b128 v[150:153], v158 offset:1024
	ds_read_b128 v[154:157], v158 offset:2048
	ds_read_b128 v[158:161], v158 offset:3072
	ds_read_b128 v[168:171], v180
	ds_read_b128 v[172:175], v180 offset:1024
	ds_read_b128 v[176:179], v180 offset:2048
	ds_read_b128 v[180:183], v180 offset:3072
	s_add_u32 s46, s44, 0xfffe0080
	s_addc_u32 s47, s45, -1
	s_cmp_eq_u32 s72, 4
	s_cselect_b32 s49, s39, s47
	s_cselect_b32 s48, s68, s46
	s_cselect_b32 s47, s37, s71
	s_cselect_b32 s46, s69, s70
	v_lshl_add_u64 v[218:219], s[44:45], 0, v[138:139]
	s_add_i32 m0, s53, 0xc000
	ds_read_b128 v[186:189], v167
	ds_read_b128 v[190:193], v167 offset:1024
	ds_read_b128 v[194:197], v167 offset:2048
	ds_read_b128 v[198:201], v167 offset:3072
	ds_read_b128 v[202:205], v167 offset:4096
	ds_read_b128 v[206:209], v167 offset:5120
	ds_read_b128 v[210:213], v167 offset:6144
	ds_read_b128 v[214:217], v167 offset:7168
	global_load_lds_dwordx4 v[218:219], off
	v_lshl_add_u64 v[218:219], s[44:45], 0, v[140:141]
	s_add_i32 m0, s53, 0xe000
	s_nop 0
	global_load_lds_dwordx4 v[218:219], off
	s_waitcnt vmcnt(8)
	s_waitcnt lgkmcnt(0)
	s_barrier
	s_setprio 1
	s_waitcnt lgkmcnt(0)
	v_mfma_f32_16x16x32_bf16 v[126:129], v[146:149], v[186:189], v[126:129]
	v_mfma_f32_16x16x32_bf16 v[122:125], v[154:157], v[186:189], v[122:125]
	v_mfma_f32_16x16x32_bf16 v[118:121], v[146:149], v[194:197], v[118:121]
	v_mfma_f32_16x16x32_bf16 v[114:117], v[154:157], v[194:197], v[114:117]
	v_mfma_f32_16x16x32_bf16 v[110:113], v[146:149], v[202:205], v[110:113]
	v_mfma_f32_16x16x32_bf16 v[106:109], v[154:157], v[202:205], v[106:109]
	v_mfma_f32_16x16x32_bf16 v[102:105], v[146:149], v[210:213], v[102:105]
	v_mfma_f32_16x16x32_bf16 v[98:101], v[154:157], v[210:213], v[98:101]
	v_mfma_f32_16x16x32_bf16 v[126:129], v[150:153], v[190:193], v[126:129]
	v_mfma_f32_16x16x32_bf16 v[122:125], v[158:161], v[190:193], v[122:125]
	v_mfma_f32_16x16x32_bf16 v[118:121], v[150:153], v[198:201], v[118:121]
	v_mfma_f32_16x16x32_bf16 v[114:117], v[158:161], v[198:201], v[114:117]
	v_mfma_f32_16x16x32_bf16 v[110:113], v[150:153], v[206:209], v[110:113]
	v_mfma_f32_16x16x32_bf16 v[106:109], v[158:161], v[206:209], v[106:109]
	v_mfma_f32_16x16x32_bf16 v[102:105], v[150:153], v[214:217], v[102:105]
	v_mfma_f32_16x16x32_bf16 v[98:101], v[158:161], v[214:217], v[98:101]
	s_setprio 0
	s_setprio 1
	v_mfma_f32_16x16x32_bf16 v[94:97], v[168:171], v[186:189], v[94:97]
	v_mfma_f32_16x16x32_bf16 v[90:93], v[176:179], v[186:189], v[90:93]
	v_mfma_f32_16x16x32_bf16 v[86:89], v[168:171], v[194:197], v[86:89]
	v_mfma_f32_16x16x32_bf16 v[82:85], v[176:179], v[194:197], v[82:85]
	v_mfma_f32_16x16x32_bf16 v[78:81], v[168:171], v[202:205], v[78:81]
	v_mfma_f32_16x16x32_bf16 v[74:77], v[176:179], v[202:205], v[74:77]
	v_mfma_f32_16x16x32_bf16 v[70:73], v[168:171], v[210:213], v[70:73]
	v_mfma_f32_16x16x32_bf16 v[66:69], v[176:179], v[210:213], v[66:69]
	v_mfma_f32_16x16x32_bf16 v[94:97], v[172:175], v[190:193], v[94:97]
	v_mfma_f32_16x16x32_bf16 v[90:93], v[180:183], v[190:193], v[90:93]
	v_mfma_f32_16x16x32_bf16 v[86:89], v[172:175], v[198:201], v[86:89]
	v_mfma_f32_16x16x32_bf16 v[82:85], v[180:183], v[198:201], v[82:85]
	v_mfma_f32_16x16x32_bf16 v[78:81], v[172:175], v[206:209], v[78:81]
	v_mfma_f32_16x16x32_bf16 v[74:77], v[180:183], v[206:209], v[74:77]
	v_mfma_f32_16x16x32_bf16 v[70:73], v[172:175], v[214:217], v[70:73]
	v_mfma_f32_16x16x32_bf16 v[66:69], v[180:183], v[214:217], v[66:69]
	s_setprio 0
	s_barrier
	s_add_i32 s73, s64, s52
	v_lshl_add_u64 v[218:219], s[46:47], 0, v[132:133]
	s_mov_b32 m0, s73
	ds_read_b128 v[186:189], v167 offset:16384
	ds_read_b128 v[190:193], v167 offset:17408
	ds_read_b128 v[194:197], v167 offset:18432
	ds_read_b128 v[198:201], v167 offset:19456
	ds_read_b128 v[202:205], v167 offset:20480
	ds_read_b128 v[206:209], v167 offset:21504
	ds_read_b128 v[210:213], v167 offset:22528
	ds_read_b128 v[214:217], v167 offset:23552
	global_load_lds_dwordx4 v[218:219], off
	s_add_i32 m0, s73, 0x2000
	s_add_u32 s74, s46, 0x20000
	v_lshl_add_u64 v[220:221], s[46:47], 0, v[136:137]
	s_addc_u32 s75, s47, 0
	s_add_i32 s73, s65, s52
	global_load_lds_dwordx4 v[220:221], off
	v_lshl_add_u64 v[222:223], s[74:75], 0, v[132:133]
	s_mov_b32 m0, s73
	v_lshl_add_u64 v[224:225], s[48:49], 0, v[134:135]
	global_load_lds_dwordx4 v[222:223], off
	v_lshl_add_u64 v[222:223], s[74:75], 0, v[136:137]
	s_add_i32 m0, s73, 0x2000
	s_nop 0
	global_load_lds_dwordx4 v[222:223], off
	v_lshl_add_u64 v[222:223], s[48:49], 0, v[130:131]
	s_mov_b32 m0, s53
	s_nop 0
	global_load_lds_dwordx4 v[222:223], off
	s_mov_b32 m0, s54
	s_nop 0
	global_load_lds_dwordx4 v[224:225], off
	s_waitcnt vmcnt(8)
	s_waitcnt lgkmcnt(0)
	s_barrier
; #define PG8_STAGE(bufoff, gbase, voff) do { _Pragma("unroll") for (int _i = 0; _i < 2; ++_i) \
;         __builtin_amdgcn_global_load_lds((const unsigned*)((const char*)(gbase) + (voff)[_i]), (LAS unsigned*)(lds + (bufoff) + ldsw + _i * 8192), 16, 0, 0); } while (0)
; #define PG8_LDA(dst, b, h) do { _Pragma("unroll") for (int m = 0; m < 4; ++m) _Pragma("unroll") for (int k = 0; k < 2; ++k) dst[m][k] = *(const LAS bf16x8*)(lds + PG8_SA(b, h) + aoff + m * 2048 + k * 1024); } while (0)
; #define PG8_LDB(dst, b, h) do { _Pragma("unroll") for (int n = 0; n < 2; ++n) _Pragma("unroll") for (int k = 0; k < 2; ++k) dst[n][k] = *(const LAS bf16x8*)(lds + PG8_SB(b, h) + boff + n * 2048 + k * 1024); } while (0)
; #define PG8_MMA(ai, bj, At, Bt) do { __builtin_amdgcn_s_setprio(1); _Pragma("unroll") for (int m = 0; m < 4; ++m) _Pragma("unroll") for (int n = 0; n < 2; ++n) _Pragma("unroll") for (int k = 0; k < 2; ++k) \
;         acc[ai][bj][m][n] = __builtin_amdgcn_mfma_f32_16x16x32_bf16(Bt[n][k], At[m][k], acc[ai][bj][m][n], 0, 0, 0); __builtin_amdgcn_s_setprio(0); } while (0)
; #define PG8_WAIT_V(n) asm volatile("s_waitcnt vmcnt(" #n ")" ::: "memory")
; #define PG8_WAIT_L(n) asm volatile("s_waitcnt lgkmcnt(" #n ")" ::: "memory")
; #define PG8_BAR __builtin_amdgcn_s_barrier()
; #define PG8_SCHED __builtin_amdgcn_sched_barrier(0)
; template <class Epi, class Sched>
; DI void gemm_phase(LAS unsigned char* lds, const Gemm g, const Sched& S, const Epi& E) {
;     ...
;             PG8_LDA(At, 0, 1); PG8_STAGE(PG8_SB(0, 0), b2, voffB); PG8_STAGE(PG8_SB(0, 1), b2 + hstepB, voffB); PG8_STAGE(PG8_SA(0, 0), a2, voffA);
;             PG8_WAIT_V(8); PG8_WAIT_L(0); PG8_BAR; PG8_MMA(1, 0, At, B0); PG8_MMA(1, 1, At, B1); PG8_BAR; PG8_SCHED;
;             PG8_LDB(B0, 1, 0); PG8_LDB(B1, 1, 1); PG8_SCHED; PG8_LDA(At, 1, 0); PG8_STAGE(PG8_SA(0, 1), a2 + hstepA, voffA);
;             PG8_WAIT_V(8); PG8_WAIT_L(0); PG8_BAR; PG8_MMA(0, 0, At, B0); PG8_MMA(0, 1, At, B1); PG8_BAR; PG8_SCHED;
	s_setprio 1
	s_waitcnt lgkmcnt(0)
	v_mfma_f32_16x16x32_bf16 v[62:65], v[146:149], v[186:189], v[62:65]
	v_mfma_f32_16x16x32_bf16 v[58:61], v[154:157], v[186:189], v[58:61]
	v_mfma_f32_16x16x32_bf16 v[54:57], v[146:149], v[194:197], v[54:57]
	v_mfma_f32_16x16x32_bf16 v[50:53], v[154:157], v[194:197], v[50:53]
	v_mfma_f32_16x16x32_bf16 v[46:49], v[146:149], v[202:205], v[46:49]
	v_mfma_f32_16x16x32_bf16 v[42:45], v[154:157], v[202:205], v[42:45]
	v_mfma_f32_16x16x32_bf16 v[38:41], v[146:149], v[210:213], v[38:41]
	v_mfma_f32_16x16x32_bf16 v[34:37], v[154:157], v[210:213], v[34:37]
	v_mfma_f32_16x16x32_bf16 v[62:65], v[150:153], v[190:193], v[62:65]
	v_mfma_f32_16x16x32_bf16 v[58:61], v[158:161], v[190:193], v[58:61]
	v_mfma_f32_16x16x32_bf16 v[54:57], v[150:153], v[198:201], v[54:57]
	v_mfma_f32_16x16x32_bf16 v[50:53], v[158:161], v[198:201], v[50:53]
	v_mfma_f32_16x16x32_bf16 v[46:49], v[150:153], v[206:209], v[46:49]
	v_mfma_f32_16x16x32_bf16 v[42:45], v[158:161], v[206:209], v[42:45]
	v_mfma_f32_16x16x32_bf16 v[38:41], v[150:153], v[214:217], v[38:41]
	v_mfma_f32_16x16x32_bf16 v[34:37], v[158:161], v[214:217], v[34:37]
	s_setprio 0
	s_setprio 1
	v_mfma_f32_16x16x32_bf16 v[30:33], v[168:171], v[186:189], v[30:33]
	v_mfma_f32_16x16x32_bf16 v[26:29], v[176:179], v[186:189], v[26:29]
	v_mfma_f32_16x16x32_bf16 v[22:25], v[168:171], v[194:197], v[22:25]
	v_mfma_f32_16x16x32_bf16 v[18:21], v[176:179], v[194:197], v[18:21]
	v_mfma_f32_16x16x32_bf16 v[14:17], v[168:171], v[202:205], v[14:17]
	v_mfma_f32_16x16x32_bf16 v[10:13], v[176:179], v[202:205], v[10:13]
	v_mfma_f32_16x16x32_bf16 v[6:9], v[168:171], v[210:213], v[6:9]
	v_mfma_f32_16x16x32_bf16 v[2:5], v[176:179], v[210:213], v[2:5]
	v_mfma_f32_16x16x32_bf16 v[30:33], v[172:175], v[190:193], v[30:33]
	v_mfma_f32_16x16x32_bf16 v[26:29], v[180:183], v[190:193], v[26:29]
	v_mfma_f32_16x16x32_bf16 v[22:25], v[172:175], v[198:201], v[22:25]
	v_mfma_f32_16x16x32_bf16 v[18:21], v[180:183], v[198:201], v[18:21]
	v_mfma_f32_16x16x32_bf16 v[14:17], v[172:175], v[206:209], v[14:17]
	v_mfma_f32_16x16x32_bf16 v[10:13], v[180:183], v[206:209], v[10:13]
	v_mfma_f32_16x16x32_bf16 v[6:9], v[172:175], v[214:217], v[6:9]
	v_mfma_f32_16x16x32_bf16 v[2:5], v[180:183], v[214:217], v[2:5]
	s_setprio 0
	s_barrier
	s_add_i32 s73, 0, 0x18000
	s_add_i32 s74, 0, 0x1c000
	v_add_u32_e32 v158, s73, v162
	v_add_u32_e32 v180, s74, v162
	ds_read_b128 v[146:149], v158
	ds_read_b128 v[150:153], v158 offset:1024
	ds_read_b128 v[154:157], v158 offset:2048
	ds_read_b128 v[158:161], v158 offset:3072
	ds_read_b128 v[168:171], v180
	ds_read_b128 v[172:175], v180 offset:1024
	ds_read_b128 v[176:179], v180 offset:2048
	ds_read_b128 v[180:183], v180 offset:3072
	s_add_u32 s48, s48, 0x20000
	s_addc_u32 s49, s49, 0
	s_mov_b32 m0, s55
	v_lshl_add_u64 v[226:227], s[48:49], 0, v[130:131]
	ds_read_b128 v[186:189], v167 offset:32768
	ds_read_b128 v[190:193], v167 offset:33792
	ds_read_b128 v[194:197], v167 offset:34816
	ds_read_b128 v[198:201], v167 offset:35840
	ds_read_b128 v[202:205], v167 offset:36864
	ds_read_b128 v[206:209], v167 offset:37888
	ds_read_b128 v[210:213], v167 offset:38912
	ds_read_b128 v[214:217], v167 offset:39936
	global_load_lds_dwordx4 v[226:227], off
	v_lshl_add_u64 v[226:227], s[48:49], 0, v[134:135]
	s_mov_b32 m0, s56
	s_nop 0
	global_load_lds_dwordx4 v[226:227], off
	s_waitcnt vmcnt(8)
	s_waitcnt lgkmcnt(0)
	s_barrier
	s_setprio 1
	s_waitcnt lgkmcnt(0)
	v_mfma_f32_16x16x32_bf16 v[126:129], v[146:149], v[186:189], v[126:129]
	v_mfma_f32_16x16x32_bf16 v[122:125], v[154:157], v[186:189], v[122:125]
	v_mfma_f32_16x16x32_bf16 v[118:121], v[146:149], v[194:197], v[118:121]
	v_mfma_f32_16x16x32_bf16 v[114:117], v[154:157], v[194:197], v[114:117]
	v_mfma_f32_16x16x32_bf16 v[110:113], v[146:149], v[202:205], v[110:113]
	v_mfma_f32_16x16x32_bf16 v[106:109], v[154:157], v[202:205], v[106:109]
	v_mfma_f32_16x16x32_bf16 v[102:105], v[146:149], v[210:213], v[102:105]
	v_mfma_f32_16x16x32_bf16 v[98:101], v[154:157], v[210:213], v[98:101]
	v_mfma_f32_16x16x32_bf16 v[126:129], v[150:153], v[190:193], v[126:129]
	v_mfma_f32_16x16x32_bf16 v[122:125], v[158:161], v[190:193], v[122:125]
	v_mfma_f32_16x16x32_bf16 v[118:121], v[150:153], v[198:201], v[118:121]
	v_mfma_f32_16x16x32_bf16 v[114:117], v[158:161], v[198:201], v[114:117]
	v_mfma_f32_16x16x32_bf16 v[110:113], v[150:153], v[206:209], v[110:113]
	v_mfma_f32_16x16x32_bf16 v[106:109], v[158:161], v[206:209], v[106:109]
	v_mfma_f32_16x16x32_bf16 v[102:105], v[150:153], v[214:217], v[102:105]
	v_mfma_f32_16x16x32_bf16 v[98:101], v[158:161], v[214:217], v[98:101]
	s_setprio 0
	s_setprio 1
	v_mfma_f32_16x16x32_bf16 v[94:97], v[168:171], v[186:189], v[94:97]
	v_mfma_f32_16x16x32_bf16 v[90:93], v[176:179], v[186:189], v[90:93]
	v_mfma_f32_16x16x32_bf16 v[86:89], v[168:171], v[194:197], v[86:89]
	v_mfma_f32_16x16x32_bf16 v[82:85], v[176:179], v[194:197], v[82:85]
	v_mfma_f32_16x16x32_bf16 v[78:81], v[168:171], v[202:205], v[78:81]
	v_mfma_f32_16x16x32_bf16 v[74:77], v[176:179], v[202:205], v[74:77]
	v_mfma_f32_16x16x32_bf16 v[70:73], v[168:171], v[210:213], v[70:73]
	v_mfma_f32_16x16x32_bf16 v[66:69], v[176:179], v[210:213], v[66:69]
	v_mfma_f32_16x16x32_bf16 v[94:97], v[172:175], v[190:193], v[94:97]
	v_mfma_f32_16x16x32_bf16 v[90:93], v[180:183], v[190:193], v[90:93]
	v_mfma_f32_16x16x32_bf16 v[86:89], v[172:175], v[198:201], v[86:89]
	v_mfma_f32_16x16x32_bf16 v[82:85], v[180:183], v[198:201], v[82:85]
	v_mfma_f32_16x16x32_bf16 v[78:81], v[172:175], v[206:209], v[78:81]
	v_mfma_f32_16x16x32_bf16 v[74:77], v[180:183], v[206:209], v[74:77]
	v_mfma_f32_16x16x32_bf16 v[70:73], v[172:175], v[214:217], v[70:73]
	v_mfma_f32_16x16x32_bf16 v[66:69], v[180:183], v[214:217], v[66:69]
	s_setprio 0
	s_barrier
; #define PG8_STAGE(bufoff, gbase, voff) do { _Pragma("unroll") for (int _i = 0; _i < 2; ++_i) \
;         __builtin_amdgcn_global_load_lds((const unsigned*)((const char*)(gbase) + (voff)[_i]), (LAS unsigned*)(lds + (bufoff) + ldsw + _i * 8192), 16, 0, 0); } while (0)
; #define PG8_LDA(dst, b, h) do { _Pragma("unroll") for (int m = 0; m < 4; ++m) _Pragma("unroll") for (int k = 0; k < 2; ++k) dst[m][k] = *(const LAS bf16x8*)(lds + PG8_SA(b, h) + aoff + m * 2048 + k * 1024); } while (0)
; #define PG8_LDB(dst, b, h) do { _Pragma("unroll") for (int n = 0; n < 2; ++n) _Pragma("unroll") for (int k = 0; k < 2; ++k) dst[n][k] = *(const LAS bf16x8*)(lds + PG8_SB(b, h) + boff + n * 2048 + k * 1024); } while (0)
; #define PG8_MMA(ai, bj, At, Bt) do { __builtin_amdgcn_s_setprio(1); _Pragma("unroll") for (int m = 0; m < 4; ++m) _Pragma("unroll") for (int n = 0; n < 2; ++n) _Pragma("unroll") for (int k = 0; k < 2; ++k) \
;         acc[ai][bj][m][n] = __builtin_amdgcn_mfma_f32_16x16x32_bf16(Bt[n][k], At[m][k], acc[ai][bj][m][n], 0, 0, 0); __builtin_amdgcn_s_setprio(0); } while (0)
; #define PG8_WAIT_V(n) asm volatile("s_waitcnt vmcnt(" #n ")" ::: "memory")
; #define PG8_WAIT_L(n) asm volatile("s_waitcnt lgkmcnt(" #n ")" ::: "memory")
; #define PG8_BAR __builtin_amdgcn_s_barrier()
; #define PG8_SCHED __builtin_amdgcn_sched_barrier(0)
; template <class Epi, class Sched>
; DI void gemm_phase(LAS unsigned char* lds, const Gemm g, const Sched& S, const Epi& E) {
;     ...
;             PG8_LDB(B0, 1, 0); PG8_LDB(B1, 1, 1); PG8_SCHED; PG8_LDA(At, 1, 0); PG8_STAGE(PG8_SA(0, 1), a2 + hstepA, voffA);
;             PG8_WAIT_V(8); PG8_WAIT_L(0); PG8_BAR; PG8_MMA(0, 0, At, B0); PG8_MMA(0, 1, At, B1); PG8_BAR; PG8_SCHED;
;             PG8_LDA(At, 1, 1); PG8_STAGE(PG8_SB(1, 0), b3, voffB); PG8_STAGE(PG8_SB(1, 1), b3 + hstepB, voffB); PG8_STAGE(PG8_SA(1, 0), a3, voffA);
;             PG8_WAIT_V(8); PG8_WAIT_L(0); PG8_BAR; PG8_MMA(1, 0, At, B0); PG8_MMA(1, 1, At, B1); PG8_BAR; PG8_SCHED;
;         }
;         if (wr == 0) PG8_BAR;
	s_add_i32 s48, s73, s52
	v_lshl_add_u64 v[218:219], v[218:219], 0, s[20:21]
	s_mov_b32 m0, s48
	ds_read_b128 v[186:189], v167 offset:49152
	ds_read_b128 v[190:193], v167 offset:50176
	ds_read_b128 v[194:197], v167 offset:51200
	ds_read_b128 v[198:201], v167 offset:52224
	ds_read_b128 v[202:205], v167 offset:53248
	ds_read_b128 v[206:209], v167 offset:54272
	ds_read_b128 v[210:213], v167 offset:55296
	ds_read_b128 v[214:217], v167 offset:56320
	global_load_lds_dwordx4 v[218:219], off
	s_add_i32 m0, s48, 0x2000
	s_add_u32 s46, s46, 0x20080
	v_lshl_add_u64 v[218:219], v[220:221], 0, s[20:21]
	s_addc_u32 s47, s47, 0
	s_add_i32 s48, s74, s52
	global_load_lds_dwordx4 v[218:219], off
	v_lshl_add_u64 v[218:219], s[46:47], 0, v[132:133]
	s_mov_b32 m0, s48
	s_nop 0
	global_load_lds_dwordx4 v[218:219], off
	v_lshl_add_u64 v[218:219], s[46:47], 0, v[136:137]
	s_add_i32 m0, s48, 0x2000
	s_nop 0
	global_load_lds_dwordx4 v[218:219], off
	v_lshl_add_u64 v[218:219], v[222:223], 0, s[20:21]
	s_mov_b32 m0, s61
	s_nop 0
	global_load_lds_dwordx4 v[218:219], off
	v_lshl_add_u64 v[218:219], v[224:225], 0, s[20:21]
	s_mov_b32 m0, s62
	s_nop 0
	global_load_lds_dwordx4 v[218:219], off
	s_waitcnt vmcnt(8)
	s_waitcnt lgkmcnt(0)
	s_barrier
	s_setprio 1
	s_waitcnt lgkmcnt(0)
	v_mfma_f32_16x16x32_bf16 v[62:65], v[146:149], v[186:189], v[62:65]
	v_mfma_f32_16x16x32_bf16 v[58:61], v[154:157], v[186:189], v[58:61]
	v_mfma_f32_16x16x32_bf16 v[54:57], v[146:149], v[194:197], v[54:57]
	v_mfma_f32_16x16x32_bf16 v[50:53], v[154:157], v[194:197], v[50:53]
	v_mfma_f32_16x16x32_bf16 v[46:49], v[146:149], v[202:205], v[46:49]
	v_mfma_f32_16x16x32_bf16 v[42:45], v[154:157], v[202:205], v[42:45]
	v_mfma_f32_16x16x32_bf16 v[38:41], v[146:149], v[210:213], v[38:41]
	v_mfma_f32_16x16x32_bf16 v[34:37], v[154:157], v[210:213], v[34:37]
	v_mfma_f32_16x16x32_bf16 v[62:65], v[150:153], v[190:193], v[62:65]
	v_mfma_f32_16x16x32_bf16 v[58:61], v[158:161], v[190:193], v[58:61]
	v_mfma_f32_16x16x32_bf16 v[54:57], v[150:153], v[198:201], v[54:57]
	v_mfma_f32_16x16x32_bf16 v[50:53], v[158:161], v[198:201], v[50:53]
	v_mfma_f32_16x16x32_bf16 v[46:49], v[150:153], v[206:209], v[46:49]
	v_mfma_f32_16x16x32_bf16 v[42:45], v[158:161], v[206:209], v[42:45]
	v_mfma_f32_16x16x32_bf16 v[38:41], v[150:153], v[214:217], v[38:41]
	v_mfma_f32_16x16x32_bf16 v[34:37], v[158:161], v[214:217], v[34:37]
	s_setprio 0
	s_setprio 1
	v_mfma_f32_16x16x32_bf16 v[30:33], v[168:171], v[186:189], v[30:33]
	v_mfma_f32_16x16x32_bf16 v[26:29], v[176:179], v[186:189], v[26:29]
	v_mfma_f32_16x16x32_bf16 v[22:25], v[168:171], v[194:197], v[22:25]
	v_mfma_f32_16x16x32_bf16 v[18:21], v[176:179], v[194:197], v[18:21]
	v_mfma_f32_16x16x32_bf16 v[14:17], v[168:171], v[202:205], v[14:17]
	v_mfma_f32_16x16x32_bf16 v[10:13], v[176:179], v[202:205], v[10:13]
	v_mfma_f32_16x16x32_bf16 v[6:9], v[168:171], v[210:213], v[6:9]
	v_mfma_f32_16x16x32_bf16 v[2:5], v[176:179], v[210:213], v[2:5]
	v_mfma_f32_16x16x32_bf16 v[30:33], v[172:175], v[190:193], v[30:33]
	v_mfma_f32_16x16x32_bf16 v[26:29], v[180:183], v[190:193], v[26:29]
	v_mfma_f32_16x16x32_bf16 v[22:25], v[172:175], v[198:201], v[22:25]
	v_mfma_f32_16x16x32_bf16 v[18:21], v[180:183], v[198:201], v[18:21]
	v_mfma_f32_16x16x32_bf16 v[14:17], v[172:175], v[206:209], v[14:17]
	v_mfma_f32_16x16x32_bf16 v[10:13], v[180:183], v[206:209], v[10:13]
	v_mfma_f32_16x16x32_bf16 v[6:9], v[172:175], v[214:217], v[6:9]
	v_mfma_f32_16x16x32_bf16 v[2:5], v[180:183], v[214:217], v[2:5]
	s_setprio 0
	s_barrier
	s_add_i32 s72, s72, 2
	s_add_u32 s44, s44, 0x100
	s_addc_u32 s45, s45, 0
	s_add_u32 s70, s70, 0x100
	s_addc_u32 s71, s71, 0
	s_cmp_gt_u32 s72, 5
	s_cbranch_scc0 .LBB0_972
	s_and_b64 vcc, exec, s[34:35]
	s_cbranch_vccz .LBB0_975
	s_barrier

;     DI bool next(int i, Unit& u) const { if (i > 0 || c >= 64) return false; u.pm = c & 31; u.pn = 0; u.src = c >> 5; return true; }
; #define PG8_STAGE(bufoff, gbase, voff) do { _Pragma("unroll") for (int _i = 0; _i < 2; ++_i) \
;         __builtin_amdgcn_global_load_lds((const unsigned*)((const char*)(gbase) + (voff)[_i]), (LAS unsigned*)(lds + (bufoff) + ldsw + _i * 8192), 16, 0, 0); } while (0)
; #define PG8_LDA(dst, b, h) do { _Pragma("unroll") for (int m = 0; m < 4; ++m) _Pragma("unroll") for (int k = 0; k < 2; ++k) dst[m][k] = *(const LAS bf16x8*)(lds + PG8_SA(b, h) + aoff + m * 2048 + k * 1024); } while (0)
; #define PG8_LDB(dst, b, h) do { _Pragma("unroll") for (int n = 0; n < 2; ++n) _Pragma("unroll") for (int k = 0; k < 2; ++k) dst[n][k] = *(const LAS bf16x8*)(lds + PG8_SB(b, h) + boff + n * 2048 + k * 1024); } while (0)
; #define PG8_WAIT_V(n) asm volatile("s_waitcnt vmcnt(" #n ")" ::: "memory")
; #define PG8_WAIT_L(n) asm volatile("s_waitcnt lgkmcnt(" #n ")" ::: "memory")
; template <class Epi, class Sched>
; DI void gemm_phase(LAS unsigned char* lds, const Gemm g, const Sched& S, const Epi& E) {
;     ...
;         const bool has_next = S.next(ui + 1, nxt);
;         E.pre(pre, cur, wr, fr);
;         const char* nA = has_next ? (const char*)(nxt.src ? g.A1 : g.A0) + (size_t)nxt.pm * tstepA : cA; const char* nB = has_next ? (const char*)(nxt.src ? g.B1 : g.B0) + (size_t)nxt.pn * tstepB : cB;
;         for (int t = 0; t < nt; t += 2) {
;             const bool last = (t == nt - 2);
;             const char* a1 = cA + (size_t)(t + 1) * kstep;
;             const char* a2 = last ? nA : cA + (size_t)(t + 2) * kstep; const char* b2 = last ? nB : cB + (size_t)(t + 2) * kstep;
;             const char* a3 = a2 + kstep; const char* b3 = b2 + kstep;
;             PG8_LDB(B0, 0, 0); PG8_LDB(B1, 0, 1); PG8_SCHED; PG8_LDA(At, 0, 0); PG8_STAGE(PG8_SA(1, 1), a1 + hstepA, voffA);
;             PG8_WAIT_V(8); PG8_WAIT_L(0); PG8_BAR; PG8_MMA(0, 0, At, B0); PG8_MMA(0, 1, At, B1); PG8_BAR; PG8_SCHED;
;     ...
;         if (!(Epi::CHAIN && cur.src == 0)) {
; #pragma unroll
;             for (int a = 0; a < 2; ++a)
; #pragma unroll
;                 for (int b = 0; b < 2; ++b)
; #pragma unroll
;                     for (int m = 0; m < 4; ++m)
; #pragma unroll
;                         for (int n = 0; n < 2; ++n) acc[a][b][m][n] = (f32x4){0.f, 0.f, 0.f, 0.f};
;         }
.LBB0_1132:
	s_ashr_i32 s35, s34, 31
	s_lshl_b64 s[36:37], s[34:35], 19
	s_add_u32 s36, s28, s36
	s_addc_u32 s37, s29, s37
	s_and_b64 s[38:39], s[6:7], exec
	s_cselect_b32 s35, s37, s45
	s_cselect_b32 s41, s36, s44
	s_ashr_i32 s21, s20, 31
	s_lshl_b64 s[38:39], s[20:21], 19
	s_add_u32 s38, s50, s38
	s_addc_u32 s39, s51, s39
	s_and_b64 s[48:49], s[6:7], exec
	s_cselect_b32 s21, s39, s47
	s_cselect_b32 s63, s38, s46
	s_add_u32 s44, s44, 0x40080
	s_addc_u32 s45, s45, 0
	s_add_u32 s64, s46, 0x100
	v_mov_b32_e32 v2, 0
	s_addc_u32 s65, s47, 0
	s_mov_b32 s66, -2
	s_waitcnt lgkmcnt(0)
	v_mov_b32_e32 v3, v2
	v_mov_b32_e32 v4, v2
	v_mov_b32_e32 v5, v2
	v_mov_b32_e32 v6, v2
	v_mov_b32_e32 v7, v2
	v_mov_b32_e32 v8, v2
	v_mov_b32_e32 v9, v2
	v_mov_b32_e32 v18, v2
	v_mov_b32_e32 v19, v2
	v_mov_b32_e32 v20, v2
	v_mov_b32_e32 v21, v2
	v_mov_b32_e32 v22, v2
	v_mov_b32_e32 v23, v2
	v_mov_b32_e32 v24, v2
	v_mov_b32_e32 v25, v2
	v_mov_b32_e32 v34, v2
	v_mov_b32_e32 v35, v2
	v_mov_b32_e32 v36, v2
	v_mov_b32_e32 v37, v2
	v_mov_b32_e32 v38, v2
	v_mov_b32_e32 v39, v2
	v_mov_b32_e32 v40, v2
	v_mov_b32_e32 v41, v2
	v_mov_b32_e32 v50, v2
	v_mov_b32_e32 v51, v2
	v_mov_b32_e32 v52, v2
	v_mov_b32_e32 v53, v2
	v_mov_b32_e32 v54, v2
	v_mov_b32_e32 v55, v2
	v_mov_b32_e32 v56, v2
	v_mov_b32_e32 v57, v2
	v_mov_b32_e32 v10, v2
	v_mov_b32_e32 v11, v2
	v_mov_b32_e32 v12, v2
	v_mov_b32_e32 v13, v2
	v_mov_b32_e32 v14, v2
	v_mov_b32_e32 v15, v2
	v_mov_b32_e32 v16, v2
	v_mov_b32_e32 v17, v2
	v_mov_b32_e32 v26, v2
	v_mov_b32_e32 v27, v2
	v_mov_b32_e32 v28, v2
	v_mov_b32_e32 v29, v2
	v_mov_b32_e32 v30, v2
	v_mov_b32_e32 v31, v2
	v_mov_b32_e32 v32, v2
	v_mov_b32_e32 v33, v2
	v_mov_b32_e32 v42, v2
	v_mov_b32_e32 v43, v2
	v_mov_b32_e32 v44, v2
	v_mov_b32_e32 v45, v2
	v_mov_b32_e32 v46, v2
	v_mov_b32_e32 v47, v2
	v_mov_b32_e32 v48, v2
	v_mov_b32_e32 v49, v2
	v_mov_b32_e32 v58, v2
	v_mov_b32_e32 v59, v2
	v_mov_b32_e32 v60, v2
	v_mov_b32_e32 v61, v2
	v_mov_b32_e32 v62, v2
	v_mov_b32_e32 v63, v2
	v_mov_b32_e32 v64, v2
	v_mov_b32_e32 v65, v2
	v_mov_b32_e32 v66, v2
	v_mov_b32_e32 v67, v2
	v_mov_b32_e32 v68, v2
	v_mov_b32_e32 v69, v2
	v_mov_b32_e32 v70, v2
	v_mov_b32_e32 v71, v2
	v_mov_b32_e32 v72, v2
	v_mov_b32_e32 v73, v2
	v_mov_b32_e32 v82, v2
	v_mov_b32_e32 v83, v2
	v_mov_b32_e32 v84, v2
	v_mov_b32_e32 v85, v2
	v_mov_b32_e32 v86, v2
	v_mov_b32_e32 v87, v2
	v_mov_b32_e32 v88, v2
	v_mov_b32_e32 v89, v2
	v_mov_b32_e32 v98, v2
	v_mov_b32_e32 v99, v2
	v_mov_b32_e32 v100, v2
	v_mov_b32_e32 v101, v2
	v_mov_b32_e32 v102, v2
	v_mov_b32_e32 v103, v2
	v_mov_b32_e32 v104, v2
	v_mov_b32_e32 v105, v2
	v_mov_b32_e32 v114, v2
	v_mov_b32_e32 v115, v2
	v_mov_b32_e32 v116, v2
	v_mov_b32_e32 v117, v2
	v_mov_b32_e32 v118, v2
	v_mov_b32_e32 v119, v2
	v_mov_b32_e32 v120, v2
	v_mov_b32_e32 v121, v2
	v_mov_b32_e32 v74, v2
	v_mov_b32_e32 v75, v2
	v_mov_b32_e32 v76, v2
	v_mov_b32_e32 v77, v2
	v_mov_b32_e32 v78, v2
	v_mov_b32_e32 v79, v2
	v_mov_b32_e32 v80, v2
	v_mov_b32_e32 v81, v2
	v_mov_b32_e32 v90, v2
	v_mov_b32_e32 v91, v2
	v_mov_b32_e32 v92, v2
	v_mov_b32_e32 v93, v2
	v_mov_b32_e32 v94, v2
	v_mov_b32_e32 v95, v2
	v_mov_b32_e32 v96, v2
	v_mov_b32_e32 v97, v2
	v_mov_b32_e32 v106, v2
	v_mov_b32_e32 v107, v2
	v_mov_b32_e32 v108, v2
	v_mov_b32_e32 v109, v2
	v_mov_b32_e32 v110, v2
	v_mov_b32_e32 v111, v2
	v_mov_b32_e32 v112, v2
	v_mov_b32_e32 v113, v2
	v_mov_b32_e32 v122, v2
	v_mov_b32_e32 v123, v2
	v_mov_b32_e32 v124, v2
	v_mov_b32_e32 v125, v2
	v_mov_b32_e32 v126, v2
	v_mov_b32_e32 v127, v2
	v_mov_b32_e32 v128, v2
	v_mov_b32_e32 v129, v2
.LBB0_1133:
	ds_read_b128 v[146:149], v152
	ds_read_b128 v[156:159], v152 offset:1024
	ds_read_b128 v[160:163], v152 offset:2048
	ds_read_b128 v[164:167], v152 offset:3072
	ds_read_b128 v[168:171], v153
	ds_read_b128 v[172:175], v153 offset:1024
	ds_read_b128 v[176:179], v153 offset:2048
	ds_read_b128 v[180:183], v153 offset:3072
	s_add_u32 s46, s44, 0xfffc0080
	s_addc_u32 s47, s45, -1
	s_cmp_eq_u32 s66, 12
	s_cselect_b32 s49, s35, s47
	s_cselect_b32 s48, s41, s46
	s_cselect_b32 s47, s21, s65
	s_cselect_b32 s46, s63, s64
	v_lshl_add_u64 v[218:219], s[44:45], 0, v[138:139]
	s_add_i32 m0, s43, 0xc000
	ds_read_b128 v[186:189], v154
	ds_read_b128 v[190:193], v154 offset:1024
	ds_read_b128 v[194:197], v154 offset:2048
	ds_read_b128 v[198:201], v154 offset:3072
	ds_read_b128 v[202:205], v154 offset:4096
	ds_read_b128 v[206:209], v154 offset:5120
	ds_read_b128 v[210:213], v154 offset:6144
	ds_read_b128 v[214:217], v154 offset:7168
	global_load_lds_dwordx4 v[218:219], off
	v_lshl_add_u64 v[218:219], s[44:45], 0, v[140:141]
	s_add_i32 m0, s43, 0xe000
	s_nop 0
	global_load_lds_dwordx4 v[218:219], off
	s_waitcnt vmcnt(8)
	s_waitcnt lgkmcnt(0)
	s_barrier
; #define PG8_STAGE(bufoff, gbase, voff) do { _Pragma("unroll") for (int _i = 0; _i < 2; ++_i) \
;         __builtin_amdgcn_global_load_lds((const unsigned*)((const char*)(gbase) + (voff)[_i]), (LAS unsigned*)(lds + (bufoff) + ldsw + _i * 8192), 16, 0, 0); } while (0)
; #define PG8_LDA(dst, b, h) do { _Pragma("unroll") for (int m = 0; m < 4; ++m) _Pragma("unroll") for (int k = 0; k < 2; ++k) dst[m][k] = *(const LAS bf16x8*)(lds + PG8_SA(b, h) + aoff + m * 2048 + k * 1024); } while (0)
; #define PG8_LDB(dst, b, h) do { _Pragma("unroll") for (int n = 0; n < 2; ++n) _Pragma("unroll") for (int k = 0; k < 2; ++k) dst[n][k] = *(const LAS bf16x8*)(lds + PG8_SB(b, h) + boff + n * 2048 + k * 1024); } while (0)
; #define PG8_MMA(ai, bj, At, Bt) do { __builtin_amdgcn_s_setprio(1); _Pragma("unroll") for (int m = 0; m < 4; ++m) _Pragma("unroll") for (int n = 0; n < 2; ++n) _Pragma("unroll") for (int k = 0; k < 2; ++k) \
;         acc[ai][bj][m][n] = __builtin_amdgcn_mfma_f32_16x16x32_bf16(Bt[n][k], At[m][k], acc[ai][bj][m][n], 0, 0, 0); __builtin_amdgcn_s_setprio(0); } while (0)
; #define PG8_WAIT_V(n) asm volatile("s_waitcnt vmcnt(" #n ")" ::: "memory")
; #define PG8_WAIT_L(n) asm volatile("s_waitcnt lgkmcnt(" #n ")" ::: "memory")
; #define PG8_BAR __builtin_amdgcn_s_barrier()
; #define PG8_SCHED __builtin_amdgcn_sched_barrier(0)
; template <class Epi, class Sched>
; DI void gemm_phase(LAS unsigned char* lds, const Gemm g, const Sched& S, const Epi& E) {
;     ...
;             PG8_LDA(At, 0, 1); PG8_STAGE(PG8_SB(0, 0), b2, voffB); PG8_STAGE(PG8_SB(0, 1), b2 + hstepB, voffB); PG8_STAGE(PG8_SA(0, 0), a2, voffA);
;             PG8_WAIT_V(8); PG8_WAIT_L(0); PG8_BAR; PG8_MMA(1, 0, At, B0); PG8_MMA(1, 1, At, B1); PG8_BAR; PG8_SCHED;
;             PG8_LDB(B0, 1, 0); PG8_LDB(B1, 1, 1); PG8_SCHED; PG8_LDA(At, 1, 0); PG8_STAGE(PG8_SA(0, 1), a2 + hstepA, voffA);
;             PG8_WAIT_V(8); PG8_WAIT_L(0); PG8_BAR; PG8_MMA(0, 0, At, B0); PG8_MMA(0, 1, At, B1); PG8_BAR; PG8_SCHED;
	s_setprio 1
	s_waitcnt lgkmcnt(0)
	v_mfma_f32_16x16x32_bf16 v[126:129], v[146:149], v[186:189], v[126:129]
	v_mfma_f32_16x16x32_bf16 v[122:125], v[160:163], v[186:189], v[122:125]
	v_mfma_f32_16x16x32_bf16 v[110:113], v[146:149], v[194:197], v[110:113]
	v_mfma_f32_16x16x32_bf16 v[106:109], v[160:163], v[194:197], v[106:109]
	v_mfma_f32_16x16x32_bf16 v[94:97], v[146:149], v[202:205], v[94:97]
	v_mfma_f32_16x16x32_bf16 v[90:93], v[160:163], v[202:205], v[90:93]
	v_mfma_f32_16x16x32_bf16 v[78:81], v[146:149], v[210:213], v[78:81]
	v_mfma_f32_16x16x32_bf16 v[74:77], v[160:163], v[210:213], v[74:77]
	v_mfma_f32_16x16x32_bf16 v[126:129], v[156:159], v[190:193], v[126:129]
	v_mfma_f32_16x16x32_bf16 v[122:125], v[164:167], v[190:193], v[122:125]
	v_mfma_f32_16x16x32_bf16 v[110:113], v[156:159], v[198:201], v[110:113]
	v_mfma_f32_16x16x32_bf16 v[106:109], v[164:167], v[198:201], v[106:109]
	v_mfma_f32_16x16x32_bf16 v[94:97], v[156:159], v[206:209], v[94:97]
	v_mfma_f32_16x16x32_bf16 v[90:93], v[164:167], v[206:209], v[90:93]
	v_mfma_f32_16x16x32_bf16 v[78:81], v[156:159], v[214:217], v[78:81]
	v_mfma_f32_16x16x32_bf16 v[74:77], v[164:167], v[214:217], v[74:77]
	s_setprio 0
	s_setprio 1
	v_mfma_f32_16x16x32_bf16 v[118:121], v[168:171], v[186:189], v[118:121]
	v_mfma_f32_16x16x32_bf16 v[114:117], v[176:179], v[186:189], v[114:117]
	v_mfma_f32_16x16x32_bf16 v[102:105], v[168:171], v[194:197], v[102:105]
	v_mfma_f32_16x16x32_bf16 v[98:101], v[176:179], v[194:197], v[98:101]
	v_mfma_f32_16x16x32_bf16 v[86:89], v[168:171], v[202:205], v[86:89]
	v_mfma_f32_16x16x32_bf16 v[82:85], v[176:179], v[202:205], v[82:85]
	v_mfma_f32_16x16x32_bf16 v[70:73], v[168:171], v[210:213], v[70:73]
	v_mfma_f32_16x16x32_bf16 v[66:69], v[176:179], v[210:213], v[66:69]
	v_mfma_f32_16x16x32_bf16 v[118:121], v[172:175], v[190:193], v[118:121]
	v_mfma_f32_16x16x32_bf16 v[114:117], v[180:183], v[190:193], v[114:117]
	v_mfma_f32_16x16x32_bf16 v[102:105], v[172:175], v[198:201], v[102:105]
	v_mfma_f32_16x16x32_bf16 v[98:101], v[180:183], v[198:201], v[98:101]
	v_mfma_f32_16x16x32_bf16 v[86:89], v[172:175], v[206:209], v[86:89]
	v_mfma_f32_16x16x32_bf16 v[82:85], v[180:183], v[206:209], v[82:85]
	v_mfma_f32_16x16x32_bf16 v[70:73], v[172:175], v[214:217], v[70:73]
	v_mfma_f32_16x16x32_bf16 v[66:69], v[180:183], v[214:217], v[66:69]
	s_setprio 0
	s_barrier
	s_add_i32 s67, s61, s52
	v_lshl_add_u64 v[218:219], s[46:47], 0, v[132:133]
	s_mov_b32 m0, s67
	ds_read_b128 v[186:189], v154 offset:16384
	ds_read_b128 v[190:193], v154 offset:17408
	ds_read_b128 v[194:197], v154 offset:18432
	ds_read_b128 v[198:201], v154 offset:19456
	ds_read_b128 v[202:205], v154 offset:20480
	ds_read_b128 v[206:209], v154 offset:21504
	ds_read_b128 v[210:213], v154 offset:22528
	ds_read_b128 v[214:217], v154 offset:23552
	global_load_lds_dwordx4 v[218:219], off
	s_add_i32 m0, s67, 0x2000
	s_add_u32 s68, s46, 0x40000
	v_lshl_add_u64 v[220:221], s[46:47], 0, v[136:137]
	s_addc_u32 s69, s47, 0
	s_add_i32 s67, s62, s52
	global_load_lds_dwordx4 v[220:221], off
	v_lshl_add_u64 v[222:223], s[68:69], 0, v[132:133]
	s_mov_b32 m0, s67
	v_lshl_add_u64 v[224:225], s[48:49], 0, v[134:135]
	global_load_lds_dwordx4 v[222:223], off
	v_lshl_add_u64 v[222:223], s[68:69], 0, v[136:137]
	s_add_i32 m0, s67, 0x2000
	s_nop 0
	global_load_lds_dwordx4 v[222:223], off
	v_lshl_add_u64 v[222:223], s[48:49], 0, v[130:131]
	s_mov_b32 m0, s43
	s_nop 0
	global_load_lds_dwordx4 v[222:223], off
	s_mov_b32 m0, s53
	s_nop 0
	global_load_lds_dwordx4 v[224:225], off
	s_waitcnt vmcnt(8)
	s_waitcnt lgkmcnt(0)
	s_barrier
	s_setprio 1
	s_waitcnt lgkmcnt(0)
	v_mfma_f32_16x16x32_bf16 v[62:65], v[146:149], v[186:189], v[62:65]
	v_mfma_f32_16x16x32_bf16 v[58:61], v[160:163], v[186:189], v[58:61]
	v_mfma_f32_16x16x32_bf16 v[46:49], v[146:149], v[194:197], v[46:49]
	v_mfma_f32_16x16x32_bf16 v[42:45], v[160:163], v[194:197], v[42:45]
	v_mfma_f32_16x16x32_bf16 v[30:33], v[146:149], v[202:205], v[30:33]
	v_mfma_f32_16x16x32_bf16 v[26:29], v[160:163], v[202:205], v[26:29]
	v_mfma_f32_16x16x32_bf16 v[14:17], v[146:149], v[210:213], v[14:17]
	v_mfma_f32_16x16x32_bf16 v[10:13], v[160:163], v[210:213], v[10:13]
	v_mfma_f32_16x16x32_bf16 v[62:65], v[156:159], v[190:193], v[62:65]
	v_mfma_f32_16x16x32_bf16 v[58:61], v[164:167], v[190:193], v[58:61]
	v_mfma_f32_16x16x32_bf16 v[46:49], v[156:159], v[198:201], v[46:49]
	v_mfma_f32_16x16x32_bf16 v[42:45], v[164:167], v[198:201], v[42:45]
	v_mfma_f32_16x16x32_bf16 v[30:33], v[156:159], v[206:209], v[30:33]
	v_mfma_f32_16x16x32_bf16 v[26:29], v[164:167], v[206:209], v[26:29]
	v_mfma_f32_16x16x32_bf16 v[14:17], v[156:159], v[214:217], v[14:17]
	v_mfma_f32_16x16x32_bf16 v[10:13], v[164:167], v[214:217], v[10:13]
	s_setprio 0
	s_setprio 1
	v_mfma_f32_16x16x32_bf16 v[54:57], v[168:171], v[186:189], v[54:57]
	v_mfma_f32_16x16x32_bf16 v[50:53], v[176:179], v[186:189], v[50:53]
	v_mfma_f32_16x16x32_bf16 v[38:41], v[168:171], v[194:197], v[38:41]
	v_mfma_f32_16x16x32_bf16 v[34:37], v[176:179], v[194:197], v[34:37]
	v_mfma_f32_16x16x32_bf16 v[22:25], v[168:171], v[202:205], v[22:25]
	v_mfma_f32_16x16x32_bf16 v[18:21], v[176:179], v[202:205], v[18:21]
	v_mfma_f32_16x16x32_bf16 v[6:9], v[168:171], v[210:213], v[6:9]
	v_mfma_f32_16x16x32_bf16 v[2:5], v[176:179], v[210:213], v[2:5]
	v_mfma_f32_16x16x32_bf16 v[54:57], v[172:175], v[190:193], v[54:57]
	v_mfma_f32_16x16x32_bf16 v[50:53], v[180:183], v[190:193], v[50:53]
	v_mfma_f32_16x16x32_bf16 v[38:41], v[172:175], v[198:201], v[38:41]
	v_mfma_f32_16x16x32_bf16 v[34:37], v[180:183], v[198:201], v[34:37]
	v_mfma_f32_16x16x32_bf16 v[22:25], v[172:175], v[206:209], v[22:25]
	v_mfma_f32_16x16x32_bf16 v[18:21], v[180:183], v[206:209], v[18:21]
	v_mfma_f32_16x16x32_bf16 v[6:9], v[172:175], v[214:217], v[6:9]
	v_mfma_f32_16x16x32_bf16 v[2:5], v[180:183], v[214:217], v[2:5]
	s_setprio 0
	s_barrier
; #define PG8_STAGE(bufoff, gbase, voff) do { _Pragma("unroll") for (int _i = 0; _i < 2; ++_i) \
;         __builtin_amdgcn_global_load_lds((const unsigned*)((const char*)(gbase) + (voff)[_i]), (LAS unsigned*)(lds + (bufoff) + ldsw + _i * 8192), 16, 0, 0); } while (0)
; #define PG8_LDA(dst, b, h) do { _Pragma("unroll") for (int m = 0; m < 4; ++m) _Pragma("unroll") for (int k = 0; k < 2; ++k) dst[m][k] = *(const LAS bf16x8*)(lds + PG8_SA(b, h) + aoff + m * 2048 + k * 1024); } while (0)
; #define PG8_LDB(dst, b, h) do { _Pragma("unroll") for (int n = 0; n < 2; ++n) _Pragma("unroll") for (int k = 0; k < 2; ++k) dst[n][k] = *(const LAS bf16x8*)(lds + PG8_SB(b, h) + boff + n * 2048 + k * 1024); } while (0)
; #define PG8_MMA(ai, bj, At, Bt) do { __builtin_amdgcn_s_setprio(1); _Pragma("unroll") for (int m = 0; m < 4; ++m) _Pragma("unroll") for (int n = 0; n < 2; ++n) _Pragma("unroll") for (int k = 0; k < 2; ++k) \
;         acc[ai][bj][m][n] = __builtin_amdgcn_mfma_f32_16x16x32_bf16(Bt[n][k], At[m][k], acc[ai][bj][m][n], 0, 0, 0); __builtin_amdgcn_s_setprio(0); } while (0)
; #define PG8_WAIT_V(n) asm volatile("s_waitcnt vmcnt(" #n ")" ::: "memory")
; #define PG8_WAIT_L(n) asm volatile("s_waitcnt lgkmcnt(" #n ")" ::: "memory")
; #define PG8_BAR __builtin_amdgcn_s_barrier()
; #define PG8_SCHED __builtin_amdgcn_sched_barrier(0)
; template <class Epi, class Sched>
; DI void gemm_phase(LAS unsigned char* lds, const Gemm g, const Sched& S, const Epi& E) {
;     ...
;             PG8_LDA(At, 0, 1); PG8_STAGE(PG8_SB(0, 0), b2, voffB); PG8_STAGE(PG8_SB(0, 1), b2 + hstepB, voffB); PG8_STAGE(PG8_SA(0, 0), a2, voffA);
;             PG8_WAIT_V(8); PG8_WAIT_L(0); PG8_BAR; PG8_MMA(1, 0, At, B0); PG8_MMA(1, 1, At, B1); PG8_BAR; PG8_SCHED;
;             PG8_LDB(B0, 1, 0); PG8_LDB(B1, 1, 1); PG8_SCHED; PG8_LDA(At, 1, 0); PG8_STAGE(PG8_SA(0, 1), a2 + hstepA, voffA);
;             PG8_WAIT_V(8); PG8_WAIT_L(0); PG8_BAR; PG8_MMA(0, 0, At, B0); PG8_MMA(0, 1, At, B1); PG8_BAR; PG8_SCHED;
	s_add_i32 s67, 0, 0x18000
	s_add_i32 s68, 0, 0x1c000
	v_add_u32_e32 v164, s67, v150
	v_add_u32_e32 v180, s68, v150
	ds_read_b128 v[146:149], v164
	ds_read_b128 v[156:159], v164 offset:1024
	ds_read_b128 v[160:163], v164 offset:2048
	ds_read_b128 v[164:167], v164 offset:3072
	ds_read_b128 v[168:171], v180
	ds_read_b128 v[172:175], v180 offset:1024
	ds_read_b128 v[176:179], v180 offset:2048
	ds_read_b128 v[180:183], v180 offset:3072
	s_add_u32 s48, s48, 0x40000
	s_addc_u32 s49, s49, 0
	s_mov_b32 m0, s54
	v_lshl_add_u64 v[226:227], s[48:49], 0, v[130:131]
	ds_read_b128 v[186:189], v154 offset:32768
	ds_read_b128 v[190:193], v154 offset:33792
	ds_read_b128 v[194:197], v154 offset:34816
	ds_read_b128 v[198:201], v154 offset:35840
	ds_read_b128 v[202:205], v154 offset:36864
	ds_read_b128 v[206:209], v154 offset:37888
	ds_read_b128 v[210:213], v154 offset:38912
	ds_read_b128 v[214:217], v154 offset:39936
	global_load_lds_dwordx4 v[226:227], off
	v_lshl_add_u64 v[226:227], s[48:49], 0, v[134:135]
	s_mov_b32 m0, s55
	s_nop 0
	global_load_lds_dwordx4 v[226:227], off
	s_waitcnt vmcnt(8)
	s_waitcnt lgkmcnt(0)
	s_barrier
	s_setprio 1
	s_waitcnt lgkmcnt(0)
	v_mfma_f32_16x16x32_bf16 v[126:129], v[146:149], v[186:189], v[126:129]
	v_mfma_f32_16x16x32_bf16 v[122:125], v[160:163], v[186:189], v[122:125]
	v_mfma_f32_16x16x32_bf16 v[110:113], v[146:149], v[194:197], v[110:113]
	v_mfma_f32_16x16x32_bf16 v[106:109], v[160:163], v[194:197], v[106:109]
	v_mfma_f32_16x16x32_bf16 v[94:97], v[146:149], v[202:205], v[94:97]
	v_mfma_f32_16x16x32_bf16 v[90:93], v[160:163], v[202:205], v[90:93]
	v_mfma_f32_16x16x32_bf16 v[78:81], v[146:149], v[210:213], v[78:81]
	v_mfma_f32_16x16x32_bf16 v[74:77], v[160:163], v[210:213], v[74:77]
	v_mfma_f32_16x16x32_bf16 v[126:129], v[156:159], v[190:193], v[126:129]
	v_mfma_f32_16x16x32_bf16 v[122:125], v[164:167], v[190:193], v[122:125]
	v_mfma_f32_16x16x32_bf16 v[110:113], v[156:159], v[198:201], v[110:113]
	v_mfma_f32_16x16x32_bf16 v[106:109], v[164:167], v[198:201], v[106:109]
	v_mfma_f32_16x16x32_bf16 v[94:97], v[156:159], v[206:209], v[94:97]
	v_mfma_f32_16x16x32_bf16 v[90:93], v[164:167], v[206:209], v[90:93]
	v_mfma_f32_16x16x32_bf16 v[78:81], v[156:159], v[214:217], v[78:81]
	v_mfma_f32_16x16x32_bf16 v[74:77], v[164:167], v[214:217], v[74:77]
	s_setprio 0
	s_setprio 1
	v_mfma_f32_16x16x32_bf16 v[118:121], v[168:171], v[186:189], v[118:121]
	v_mfma_f32_16x16x32_bf16 v[114:117], v[176:179], v[186:189], v[114:117]
	v_mfma_f32_16x16x32_bf16 v[102:105], v[168:171], v[194:197], v[102:105]
	v_mfma_f32_16x16x32_bf16 v[98:101], v[176:179], v[194:197], v[98:101]
	v_mfma_f32_16x16x32_bf16 v[86:89], v[168:171], v[202:205], v[86:89]
	v_mfma_f32_16x16x32_bf16 v[82:85], v[176:179], v[202:205], v[82:85]
	v_mfma_f32_16x16x32_bf16 v[70:73], v[168:171], v[210:213], v[70:73]
	v_mfma_f32_16x16x32_bf16 v[66:69], v[176:179], v[210:213], v[66:69]
	v_mfma_f32_16x16x32_bf16 v[118:121], v[172:175], v[190:193], v[118:121]
	v_mfma_f32_16x16x32_bf16 v[114:117], v[180:183], v[190:193], v[114:117]
	v_mfma_f32_16x16x32_bf16 v[102:105], v[172:175], v[198:201], v[102:105]
	v_mfma_f32_16x16x32_bf16 v[98:101], v[180:183], v[198:201], v[98:101]
	v_mfma_f32_16x16x32_bf16 v[86:89], v[172:175], v[206:209], v[86:89]
	v_mfma_f32_16x16x32_bf16 v[82:85], v[180:183], v[206:209], v[82:85]
	v_mfma_f32_16x16x32_bf16 v[70:73], v[172:175], v[214:217], v[70:73]
	v_mfma_f32_16x16x32_bf16 v[66:69], v[180:183], v[214:217], v[66:69]
	s_setprio 0
	s_barrier
; #define PG8_STAGE(bufoff, gbase, voff) do { _Pragma("unroll") for (int _i = 0; _i < 2; ++_i) \
;         __builtin_amdgcn_global_load_lds((const unsigned*)((const char*)(gbase) + (voff)[_i]), (LAS unsigned*)(lds + (bufoff) + ldsw + _i * 8192), 16, 0, 0); } while (0)
; #define PG8_LDA(dst, b, h) do { _Pragma("unroll") for (int m = 0; m < 4; ++m) _Pragma("unroll") for (int k = 0; k < 2; ++k) dst[m][k] = *(const LAS bf16x8*)(lds + PG8_SA(b, h) + aoff + m * 2048 + k * 1024); } while (0)
; #define PG8_LDB(dst, b, h) do { _Pragma("unroll") for (int n = 0; n < 2; ++n) _Pragma("unroll") for (int k = 0; k < 2; ++k) dst[n][k] = *(const LAS bf16x8*)(lds + PG8_SB(b, h) + boff + n * 2048 + k * 1024); } while (0)
; #define PG8_MMA(ai, bj, At, Bt) do { __builtin_amdgcn_s_setprio(1); _Pragma("unroll") for (int m = 0; m < 4; ++m) _Pragma("unroll") for (int n = 0; n < 2; ++n) _Pragma("unroll") for (int k = 0; k < 2; ++k) \
;         acc[ai][bj][m][n] = __builtin_amdgcn_mfma_f32_16x16x32_bf16(Bt[n][k], At[m][k], acc[ai][bj][m][n], 0, 0, 0); __builtin_amdgcn_s_setprio(0); } while (0)
; #define PG8_WAIT_V(n) asm volatile("s_waitcnt vmcnt(" #n ")" ::: "memory")
; #define PG8_WAIT_L(n) asm volatile("s_waitcnt lgkmcnt(" #n ")" ::: "memory")
; #define PG8_BAR __builtin_amdgcn_s_barrier()
; #define PG8_SCHED __builtin_amdgcn_sched_barrier(0)
; template <class Epi, class Sched>
; DI void gemm_phase(LAS unsigned char* lds, const Gemm g, const Sched& S, const Epi& E) {
;     ...
;             PG8_LDB(B0, 1, 0); PG8_LDB(B1, 1, 1); PG8_SCHED; PG8_LDA(At, 1, 0); PG8_STAGE(PG8_SA(0, 1), a2 + hstepA, voffA);
;             PG8_WAIT_V(8); PG8_WAIT_L(0); PG8_BAR; PG8_MMA(0, 0, At, B0); PG8_MMA(0, 1, At, B1); PG8_BAR; PG8_SCHED;
;             PG8_LDA(At, 1, 1); PG8_STAGE(PG8_SB(1, 0), b3, voffB); PG8_STAGE(PG8_SB(1, 1), b3 + hstepB, voffB); PG8_STAGE(PG8_SA(1, 0), a3, voffA);
;             PG8_WAIT_V(8); PG8_WAIT_L(0); PG8_BAR; PG8_MMA(1, 0, At, B0); PG8_MMA(1, 1, At, B1); PG8_BAR; PG8_SCHED;
;         }
;         if (wr == 0) PG8_BAR;
	s_add_i32 s48, s67, s52
	v_lshl_add_u64 v[218:219], v[218:219], 0, s[16:17]
	s_mov_b32 m0, s48
	ds_read_b128 v[186:189], v154 offset:49152
	ds_read_b128 v[190:193], v154 offset:50176
	ds_read_b128 v[194:197], v154 offset:51200
	ds_read_b128 v[198:201], v154 offset:52224
	ds_read_b128 v[202:205], v154 offset:53248
	ds_read_b128 v[206:209], v154 offset:54272
	ds_read_b128 v[210:213], v154 offset:55296
	ds_read_b128 v[214:217], v154 offset:56320
	global_load_lds_dwordx4 v[218:219], off
	s_add_i32 m0, s48, 0x2000
	s_add_u32 s46, s46, 0x40080
	v_lshl_add_u64 v[218:219], v[220:221], 0, s[16:17]
	s_addc_u32 s47, s47, 0
	s_add_i32 s48, s68, s52
	global_load_lds_dwordx4 v[218:219], off
	v_lshl_add_u64 v[218:219], s[46:47], 0, v[132:133]
	s_mov_b32 m0, s48
	s_nop 0
	global_load_lds_dwordx4 v[218:219], off
	v_lshl_add_u64 v[218:219], s[46:47], 0, v[136:137]
	s_add_i32 m0, s48, 0x2000
	s_nop 0
	global_load_lds_dwordx4 v[218:219], off
	v_lshl_add_u64 v[218:219], v[222:223], 0, s[16:17]
	s_mov_b32 m0, s57
	s_nop 0
	global_load_lds_dwordx4 v[218:219], off
	v_lshl_add_u64 v[218:219], v[224:225], 0, s[16:17]
	s_mov_b32 m0, s58
	s_nop 0
	global_load_lds_dwordx4 v[218:219], off
	s_waitcnt vmcnt(8)
	s_waitcnt lgkmcnt(0)
	s_barrier
	s_setprio 1
	s_waitcnt lgkmcnt(0)
	v_mfma_f32_16x16x32_bf16 v[62:65], v[146:149], v[186:189], v[62:65]
	v_mfma_f32_16x16x32_bf16 v[58:61], v[160:163], v[186:189], v[58:61]
	v_mfma_f32_16x16x32_bf16 v[46:49], v[146:149], v[194:197], v[46:49]
	v_mfma_f32_16x16x32_bf16 v[42:45], v[160:163], v[194:197], v[42:45]
	v_mfma_f32_16x16x32_bf16 v[30:33], v[146:149], v[202:205], v[30:33]
	v_mfma_f32_16x16x32_bf16 v[26:29], v[160:163], v[202:205], v[26:29]
	v_mfma_f32_16x16x32_bf16 v[14:17], v[146:149], v[210:213], v[14:17]
	v_mfma_f32_16x16x32_bf16 v[10:13], v[160:163], v[210:213], v[10:13]
	v_mfma_f32_16x16x32_bf16 v[62:65], v[156:159], v[190:193], v[62:65]
	v_mfma_f32_16x16x32_bf16 v[58:61], v[164:167], v[190:193], v[58:61]
	v_mfma_f32_16x16x32_bf16 v[46:49], v[156:159], v[198:201], v[46:49]
	v_mfma_f32_16x16x32_bf16 v[42:45], v[164:167], v[198:201], v[42:45]
	v_mfma_f32_16x16x32_bf16 v[30:33], v[156:159], v[206:209], v[30:33]
	v_mfma_f32_16x16x32_bf16 v[26:29], v[164:167], v[206:209], v[26:29]
	v_mfma_f32_16x16x32_bf16 v[14:17], v[156:159], v[214:217], v[14:17]
	v_mfma_f32_16x16x32_bf16 v[10:13], v[164:167], v[214:217], v[10:13]
	s_setprio 0
	s_setprio 1
	v_mfma_f32_16x16x32_bf16 v[54:57], v[168:171], v[186:189], v[54:57]
	v_mfma_f32_16x16x32_bf16 v[50:53], v[176:179], v[186:189], v[50:53]
	v_mfma_f32_16x16x32_bf16 v[38:41], v[168:171], v[194:197], v[38:41]
	v_mfma_f32_16x16x32_bf16 v[34:37], v[176:179], v[194:197], v[34:37]
	v_mfma_f32_16x16x32_bf16 v[22:25], v[168:171], v[202:205], v[22:25]
	v_mfma_f32_16x16x32_bf16 v[18:21], v[176:179], v[202:205], v[18:21]
	v_mfma_f32_16x16x32_bf16 v[6:9], v[168:171], v[210:213], v[6:9]
	v_mfma_f32_16x16x32_bf16 v[2:5], v[176:179], v[210:213], v[2:5]
	v_mfma_f32_16x16x32_bf16 v[54:57], v[172:175], v[190:193], v[54:57]
	v_mfma_f32_16x16x32_bf16 v[50:53], v[180:183], v[190:193], v[50:53]
	v_mfma_f32_16x16x32_bf16 v[38:41], v[172:175], v[198:201], v[38:41]
	v_mfma_f32_16x16x32_bf16 v[34:37], v[180:183], v[198:201], v[34:37]
	v_mfma_f32_16x16x32_bf16 v[22:25], v[172:175], v[206:209], v[22:25]
	v_mfma_f32_16x16x32_bf16 v[18:21], v[180:183], v[206:209], v[18:21]
	v_mfma_f32_16x16x32_bf16 v[6:9], v[172:175], v[214:217], v[6:9]
	v_mfma_f32_16x16x32_bf16 v[2:5], v[180:183], v[214:217], v[2:5]
	s_setprio 0
	s_barrier
	s_add_i32 s66, s66, 2
	s_add_u32 s44, s44, 0x100
	s_addc_u32 s45, s45, 0
	s_add_u32 s64, s64, 0x100
	s_addc_u32 s65, s65, 0
	s_cmp_gt_u32 s66, 13
	s_cbranch_scc0 .LBB0_1133
	s_and_b64 vcc, exec, s[18:19]
	s_cbranch_vccz .LBB0_1136
	s_barrier

; template <class Epi, class Sched>
; DI void gemm_phase(LAS unsigned char* lds, const Gemm g, const Sched& S, const Epi& E) {
;     ...
;         if (!(Epi::CHAIN && cur.src == 0)) {
; #pragma unroll
;             for (int a = 0; a < 2; ++a)
; #pragma unroll
;                 for (int b = 0; b < 2; ++b)
; #pragma unroll
;                     for (int m = 0; m < 4; ++m)
; #pragma unroll
;                         for (int n = 0; n < 2; ++n) acc[a][b][m][n] = (f32x4){0.f, 0.f, 0.f, 0.f};
;         }
; DI void load_rows(PreRows& pr, const float* ssq, const pg8::Unit& u, int wr, int fr) {
; #pragma unroll
;     for (int ai = 0; ai < 2; ++ai)
; #pragma unroll
;         for (int m = 0; m < 4; ++m) pr.v[ai * 4 + m] = ssq[u.pm * 256 + ai * 128 + wr * 64 + m * 16 + fr];
; }
.LBB0_1233:
	v_lshl_add_u32 v154, s44, 8, v1
	v_ashrrev_i32_e32 v155, 31, v154
	v_add_u32_e32 v152, 0x80, v154
	v_add_u32_e32 v150, 0x90, v154
	v_add_u32_e32 v148, 0xa0, v154
	v_add_u32_e32 v146, 0xb0, v154
	v_lshl_add_u64 v[2:3], v[154:155], 2, s[8:9]
	v_ashrrev_i32_e32 v153, 31, v152
	v_ashrrev_i32_e32 v151, 31, v150
	v_ashrrev_i32_e32 v149, 31, v148
	v_ashrrev_i32_e32 v147, 31, v146
	v_lshl_add_u64 v[4:5], v[152:153], 2, s[8:9]
	v_lshl_add_u64 v[6:7], v[150:151], 2, s[8:9]
	v_lshl_add_u64 v[8:9], v[148:149], 2, s[8:9]
	v_lshl_add_u64 v[10:11], v[146:147], 2, s[8:9]
	global_load_dword v164, v[2:3], off
	global_load_dword v163, v[2:3], off offset:64
	global_load_dword v162, v[2:3], off offset:128
	global_load_dword v155, v[2:3], off offset:192
	global_load_dword v153, v[4:5], off
	global_load_dword v151, v[6:7], off
	global_load_dword v149, v[8:9], off
	global_load_dword v147, v[10:11], off
	s_ashr_i32 s35, s34, 31
	s_lshl_b64 s[36:37], s[34:35], 19
	s_add_u32 s36, s30, s36
	s_addc_u32 s37, s31, s37
	s_and_b64 s[38:39], s[4:5], exec
	s_cselect_b32 s35, s37, s41
	s_cselect_b32 s61, s36, s40
	s_ashr_i32 s21, s20, 31
	s_lshl_b64 s[38:39], s[20:21], 19
	s_add_u32 s38, s28, s38
	s_addc_u32 s39, s29, s39
	s_and_b64 s[44:45], s[4:5], exec
	s_cselect_b32 s21, s39, s43
	s_cselect_b32 s62, s38, s42
	s_add_u32 s40, s40, 0x40080
	s_addc_u32 s41, s41, 0
	s_add_u32 s63, s42, 0x100
	v_mov_b32_e32 v2, 0
	s_addc_u32 s64, s43, 0
	s_mov_b32 s65, -2
	v_mov_b32_e32 v3, v2
	v_mov_b32_e32 v4, v2
	v_mov_b32_e32 v5, v2
	v_mov_b32_e32 v10, v2
	v_mov_b32_e32 v11, v2
	v_mov_b32_e32 v12, v2
	v_mov_b32_e32 v13, v2
	v_mov_b32_e32 v18, v2
	v_mov_b32_e32 v19, v2
	v_mov_b32_e32 v20, v2
	v_mov_b32_e32 v21, v2
	v_mov_b32_e32 v26, v2
	v_mov_b32_e32 v27, v2
	v_mov_b32_e32 v28, v2
	v_mov_b32_e32 v29, v2
	v_mov_b32_e32 v34, v2
	v_mov_b32_e32 v35, v2
	v_mov_b32_e32 v36, v2
	v_mov_b32_e32 v37, v2
	v_mov_b32_e32 v42, v2
	v_mov_b32_e32 v43, v2
	v_mov_b32_e32 v44, v2
	v_mov_b32_e32 v45, v2
	v_mov_b32_e32 v50, v2
	v_mov_b32_e32 v51, v2
	v_mov_b32_e32 v52, v2
	v_mov_b32_e32 v53, v2
	v_mov_b32_e32 v58, v2
	v_mov_b32_e32 v59, v2
	v_mov_b32_e32 v60, v2
	v_mov_b32_e32 v61, v2
	v_mov_b32_e32 v6, v2
	v_mov_b32_e32 v7, v2
	v_mov_b32_e32 v8, v2
	v_mov_b32_e32 v9, v2
	v_mov_b32_e32 v14, v2
	v_mov_b32_e32 v15, v2
	v_mov_b32_e32 v16, v2
	v_mov_b32_e32 v17, v2
	v_mov_b32_e32 v22, v2
	v_mov_b32_e32 v23, v2
	v_mov_b32_e32 v24, v2
	v_mov_b32_e32 v25, v2
	v_mov_b32_e32 v30, v2
	v_mov_b32_e32 v31, v2
	v_mov_b32_e32 v32, v2
	v_mov_b32_e32 v33, v2
	v_mov_b32_e32 v38, v2
	v_mov_b32_e32 v39, v2
	v_mov_b32_e32 v40, v2
	v_mov_b32_e32 v41, v2
	v_mov_b32_e32 v46, v2
	v_mov_b32_e32 v47, v2
	v_mov_b32_e32 v48, v2
	v_mov_b32_e32 v49, v2
	v_mov_b32_e32 v54, v2
	v_mov_b32_e32 v55, v2
	v_mov_b32_e32 v56, v2
	v_mov_b32_e32 v57, v2
	v_mov_b32_e32 v62, v2
	v_mov_b32_e32 v63, v2
	v_mov_b32_e32 v64, v2
	v_mov_b32_e32 v65, v2
	v_mov_b32_e32 v66, v2
	v_mov_b32_e32 v67, v2
	v_mov_b32_e32 v68, v2
	v_mov_b32_e32 v69, v2
	v_mov_b32_e32 v74, v2
	v_mov_b32_e32 v75, v2
	v_mov_b32_e32 v76, v2
	v_mov_b32_e32 v77, v2
	v_mov_b32_e32 v82, v2
	v_mov_b32_e32 v83, v2
	v_mov_b32_e32 v84, v2
	v_mov_b32_e32 v85, v2
	v_mov_b32_e32 v90, v2
	v_mov_b32_e32 v91, v2
	v_mov_b32_e32 v92, v2
	v_mov_b32_e32 v93, v2
	v_mov_b32_e32 v98, v2
	v_mov_b32_e32 v99, v2
	v_mov_b32_e32 v100, v2
	v_mov_b32_e32 v101, v2
	v_mov_b32_e32 v106, v2
	v_mov_b32_e32 v107, v2
	v_mov_b32_e32 v108, v2
	v_mov_b32_e32 v109, v2
	v_mov_b32_e32 v114, v2
	v_mov_b32_e32 v115, v2
	v_mov_b32_e32 v116, v2
	v_mov_b32_e32 v117, v2
	v_mov_b32_e32 v122, v2
	v_mov_b32_e32 v123, v2
	v_mov_b32_e32 v124, v2
	v_mov_b32_e32 v125, v2
	v_mov_b32_e32 v70, v2
	v_mov_b32_e32 v71, v2
	v_mov_b32_e32 v72, v2
	v_mov_b32_e32 v73, v2
	v_mov_b32_e32 v78, v2
	v_mov_b32_e32 v79, v2
	v_mov_b32_e32 v80, v2
	v_mov_b32_e32 v81, v2
	v_mov_b32_e32 v86, v2
	v_mov_b32_e32 v87, v2
	v_mov_b32_e32 v88, v2
	v_mov_b32_e32 v89, v2
	v_mov_b32_e32 v94, v2
	v_mov_b32_e32 v95, v2
	v_mov_b32_e32 v96, v2
	v_mov_b32_e32 v97, v2
	v_mov_b32_e32 v102, v2
	v_mov_b32_e32 v103, v2
	v_mov_b32_e32 v104, v2
	v_mov_b32_e32 v105, v2
	v_mov_b32_e32 v110, v2
	v_mov_b32_e32 v111, v2
	v_mov_b32_e32 v112, v2
	v_mov_b32_e32 v113, v2
	v_mov_b32_e32 v118, v2
	v_mov_b32_e32 v119, v2
	v_mov_b32_e32 v120, v2
	v_mov_b32_e32 v121, v2
	v_mov_b32_e32 v126, v2
	v_mov_b32_e32 v127, v2
	v_mov_b32_e32 v128, v2
	v_mov_b32_e32 v129, v2
; #define PG8_STAGE(bufoff, gbase, voff) do { _Pragma("unroll") for (int _i = 0; _i < 2; ++_i) \
;         __builtin_amdgcn_global_load_lds((const unsigned*)((const char*)(gbase) + (voff)[_i]), (LAS unsigned*)(lds + (bufoff) + ldsw + _i * 8192), 16, 0, 0); } while (0)
; #define PG8_LDA(dst, b, h) do { _Pragma("unroll") for (int m = 0; m < 4; ++m) _Pragma("unroll") for (int k = 0; k < 2; ++k) dst[m][k] = *(const LAS bf16x8*)(lds + PG8_SA(b, h) + aoff + m * 2048 + k * 1024); } while (0)
; #define PG8_LDB(dst, b, h) do { _Pragma("unroll") for (int n = 0; n < 2; ++n) _Pragma("unroll") for (int k = 0; k < 2; ++k) dst[n][k] = *(const LAS bf16x8*)(lds + PG8_SB(b, h) + boff + n * 2048 + k * 1024); } while (0)
; #define PG8_MMA(ai, bj, At, Bt) do { __builtin_amdgcn_s_setprio(1); _Pragma("unroll") for (int m = 0; m < 4; ++m) _Pragma("unroll") for (int n = 0; n < 2; ++n) _Pragma("unroll") for (int k = 0; k < 2; ++k) \
;         acc[ai][bj][m][n] = __builtin_amdgcn_mfma_f32_16x16x32_bf16(Bt[n][k], At[m][k], acc[ai][bj][m][n], 0, 0, 0); __builtin_amdgcn_s_setprio(0); } while (0)
; #define PG8_WAIT_V(n) asm volatile("s_waitcnt vmcnt(" #n ")" ::: "memory")
; #define PG8_WAIT_L(n) asm volatile("s_waitcnt lgkmcnt(" #n ")" ::: "memory")
; #define PG8_BAR __builtin_amdgcn_s_barrier()
; #define PG8_SCHED __builtin_amdgcn_sched_barrier(0)
; template <class Epi, class Sched>
; DI void gemm_phase(LAS unsigned char* lds, const Gemm g, const Sched& S, const Epi& E) {
;     ...
;         for (int t = 0; t < nt; t += 2) {
;             const bool last = (t == nt - 2);
;             const char* a1 = cA + (size_t)(t + 1) * kstep;
;             const char* a2 = last ? nA : cA + (size_t)(t + 2) * kstep; const char* b2 = last ? nB : cB + (size_t)(t + 2) * kstep;
;             const char* a3 = a2 + kstep; const char* b3 = b2 + kstep;
;             PG8_LDB(B0, 0, 0); PG8_LDB(B1, 0, 1); PG8_SCHED; PG8_LDA(At, 0, 0); PG8_STAGE(PG8_SA(1, 1), a1 + hstepA, voffA);
;             PG8_WAIT_V(8); PG8_WAIT_L(0); PG8_BAR; PG8_MMA(0, 0, At, B0); PG8_MMA(0, 1, At, B1); PG8_BAR; PG8_SCHED;
;             PG8_LDA(At, 0, 1); PG8_STAGE(PG8_SB(0, 0), b2, voffB); PG8_STAGE(PG8_SB(0, 1), b2 + hstepB, voffB); PG8_STAGE(PG8_SA(0, 0), a2, voffA);
;             PG8_WAIT_V(8); PG8_WAIT_L(0); PG8_BAR; PG8_MMA(1, 0, At, B0); PG8_MMA(1, 1, At, B1); PG8_BAR; PG8_SCHED;
.LBB0_1234:
	ds_read_b128 v[166:169], v160
	ds_read_b128 v[170:173], v160 offset:1024
	ds_read_b128 v[174:177], v160 offset:2048
	ds_read_b128 v[178:181], v160 offset:3072
	ds_read_b128 v[186:189], v161
	ds_read_b128 v[190:193], v161 offset:1024
	ds_read_b128 v[194:197], v161 offset:2048
	ds_read_b128 v[198:201], v161 offset:3072
	s_add_u32 s42, s40, 0xfffc0080
	s_addc_u32 s43, s41, -1
	s_cmp_eq_u32 s65, 12
	s_cselect_b32 s45, s35, s43
	s_cselect_b32 s44, s61, s42
	s_cselect_b32 s43, s21, s64
	s_cselect_b32 s42, s62, s63
	v_lshl_add_u64 v[182:183], s[40:41], 0, v[138:139]
	s_add_i32 m0, s49, 0xc000
	ds_read_b128 v[202:205], v158
	ds_read_b128 v[206:209], v158 offset:1024
	ds_read_b128 v[210:213], v158 offset:2048
	ds_read_b128 v[214:217], v158 offset:3072
	ds_read_b128 v[218:221], v158 offset:4096
	ds_read_b128 v[222:225], v158 offset:5120
	ds_read_b128 v[226:229], v158 offset:6144
	ds_read_b128 v[230:233], v158 offset:7168
	global_load_lds_dwordx4 v[182:183], off
	v_lshl_add_u64 v[182:183], s[40:41], 0, v[140:141]
	s_add_i32 m0, s49, 0xe000
	s_nop 0
	global_load_lds_dwordx4 v[182:183], off
	s_waitcnt vmcnt(8)
	s_waitcnt lgkmcnt(0)
	s_barrier
	s_setprio 1
	s_waitcnt lgkmcnt(0)
	v_mfma_f32_16x16x32_bf16 v[126:129], v[166:169], v[202:205], v[126:129]
	v_mfma_f32_16x16x32_bf16 v[118:121], v[174:177], v[202:205], v[118:121]
	v_mfma_f32_16x16x32_bf16 v[110:113], v[166:169], v[210:213], v[110:113]
	v_mfma_f32_16x16x32_bf16 v[102:105], v[174:177], v[210:213], v[102:105]
	v_mfma_f32_16x16x32_bf16 v[94:97], v[166:169], v[218:221], v[94:97]
	v_mfma_f32_16x16x32_bf16 v[86:89], v[174:177], v[218:221], v[86:89]
	v_mfma_f32_16x16x32_bf16 v[78:81], v[166:169], v[226:229], v[78:81]
	v_mfma_f32_16x16x32_bf16 v[70:73], v[174:177], v[226:229], v[70:73]
	v_mfma_f32_16x16x32_bf16 v[126:129], v[170:173], v[206:209], v[126:129]
	v_mfma_f32_16x16x32_bf16 v[118:121], v[178:181], v[206:209], v[118:121]
	v_mfma_f32_16x16x32_bf16 v[110:113], v[170:173], v[214:217], v[110:113]
	v_mfma_f32_16x16x32_bf16 v[102:105], v[178:181], v[214:217], v[102:105]
	v_mfma_f32_16x16x32_bf16 v[94:97], v[170:173], v[222:225], v[94:97]
	v_mfma_f32_16x16x32_bf16 v[86:89], v[178:181], v[222:225], v[86:89]
	v_mfma_f32_16x16x32_bf16 v[78:81], v[170:173], v[230:233], v[78:81]
	v_mfma_f32_16x16x32_bf16 v[70:73], v[178:181], v[230:233], v[70:73]
	s_setprio 0
	s_setprio 1
	v_mfma_f32_16x16x32_bf16 v[122:125], v[186:189], v[202:205], v[122:125]
	v_mfma_f32_16x16x32_bf16 v[114:117], v[194:197], v[202:205], v[114:117]
	v_mfma_f32_16x16x32_bf16 v[106:109], v[186:189], v[210:213], v[106:109]
	v_mfma_f32_16x16x32_bf16 v[98:101], v[194:197], v[210:213], v[98:101]
	v_mfma_f32_16x16x32_bf16 v[90:93], v[186:189], v[218:221], v[90:93]
	v_mfma_f32_16x16x32_bf16 v[82:85], v[194:197], v[218:221], v[82:85]
	v_mfma_f32_16x16x32_bf16 v[74:77], v[186:189], v[226:229], v[74:77]
	v_mfma_f32_16x16x32_bf16 v[66:69], v[194:197], v[226:229], v[66:69]
	v_mfma_f32_16x16x32_bf16 v[122:125], v[190:193], v[206:209], v[122:125]
	v_mfma_f32_16x16x32_bf16 v[114:117], v[198:201], v[206:209], v[114:117]
	v_mfma_f32_16x16x32_bf16 v[106:109], v[190:193], v[214:217], v[106:109]
	v_mfma_f32_16x16x32_bf16 v[98:101], v[198:201], v[214:217], v[98:101]
	v_mfma_f32_16x16x32_bf16 v[90:93], v[190:193], v[222:225], v[90:93]
	v_mfma_f32_16x16x32_bf16 v[82:85], v[198:201], v[222:225], v[82:85]
	v_mfma_f32_16x16x32_bf16 v[74:77], v[190:193], v[230:233], v[74:77]
	v_mfma_f32_16x16x32_bf16 v[66:69], v[198:201], v[230:233], v[66:69]
	s_setprio 0
	s_barrier
	s_add_i32 s66, s57, s46
	v_lshl_add_u64 v[182:183], s[42:43], 0, v[134:135]
	s_mov_b32 m0, s66
	ds_read_b128 v[202:205], v158 offset:16384
	ds_read_b128 v[206:209], v158 offset:17408
	ds_read_b128 v[210:213], v158 offset:18432
	ds_read_b128 v[214:217], v158 offset:19456
	ds_read_b128 v[218:221], v158 offset:20480
	ds_read_b128 v[222:225], v158 offset:21504
	ds_read_b128 v[226:229], v158 offset:22528
	ds_read_b128 v[230:233], v158 offset:23552
	global_load_lds_dwordx4 v[182:183], off
	s_add_i32 m0, s66, 0x2000
	s_add_u32 s66, s42, 0x40000
	v_lshl_add_u64 v[234:235], s[42:43], 0, v[130:131]
	s_addc_u32 s67, s43, 0
	s_add_i32 s68, s58, s46
	global_load_lds_dwordx4 v[234:235], off
	v_lshl_add_u64 v[236:237], s[66:67], 0, v[134:135]
	s_mov_b32 m0, s68
	v_lshl_add_u64 v[238:239], s[44:45], 0, v[132:133]
	global_load_lds_dwordx4 v[236:237], off
	v_lshl_add_u64 v[236:237], s[66:67], 0, v[130:131]
	s_add_i32 m0, s68, 0x2000
	s_nop 0
	global_load_lds_dwordx4 v[236:237], off
	v_lshl_add_u64 v[236:237], s[44:45], 0, v[136:137]
	s_mov_b32 m0, s49
	s_nop 0
	global_load_lds_dwordx4 v[236:237], off
	s_mov_b32 m0, s50
	s_nop 0
	global_load_lds_dwordx4 v[238:239], off
	s_waitcnt vmcnt(8)
	s_waitcnt lgkmcnt(0)
	s_barrier
; #define PG8_STAGE(bufoff, gbase, voff) do { _Pragma("unroll") for (int _i = 0; _i < 2; ++_i) \
;         __builtin_amdgcn_global_load_lds((const unsigned*)((const char*)(gbase) + (voff)[_i]), (LAS unsigned*)(lds + (bufoff) + ldsw + _i * 8192), 16, 0, 0); } while (0)
; #define PG8_LDA(dst, b, h) do { _Pragma("unroll") for (int m = 0; m < 4; ++m) _Pragma("unroll") for (int k = 0; k < 2; ++k) dst[m][k] = *(const LAS bf16x8*)(lds + PG8_SA(b, h) + aoff + m * 2048 + k * 1024); } while (0)
; #define PG8_LDB(dst, b, h) do { _Pragma("unroll") for (int n = 0; n < 2; ++n) _Pragma("unroll") for (int k = 0; k < 2; ++k) dst[n][k] = *(const LAS bf16x8*)(lds + PG8_SB(b, h) + boff + n * 2048 + k * 1024); } while (0)
; #define PG8_MMA(ai, bj, At, Bt) do { __builtin_amdgcn_s_setprio(1); _Pragma("unroll") for (int m = 0; m < 4; ++m) _Pragma("unroll") for (int n = 0; n < 2; ++n) _Pragma("unroll") for (int k = 0; k < 2; ++k) \
;         acc[ai][bj][m][n] = __builtin_amdgcn_mfma_f32_16x16x32_bf16(Bt[n][k], At[m][k], acc[ai][bj][m][n], 0, 0, 0); __builtin_amdgcn_s_setprio(0); } while (0)
; #define PG8_WAIT_V(n) asm volatile("s_waitcnt vmcnt(" #n ")" ::: "memory")
; #define PG8_WAIT_L(n) asm volatile("s_waitcnt lgkmcnt(" #n ")" ::: "memory")
; #define PG8_BAR __builtin_amdgcn_s_barrier()
; #define PG8_SCHED __builtin_amdgcn_sched_barrier(0)
; template <class Epi, class Sched>
; DI void gemm_phase(LAS unsigned char* lds, const Gemm g, const Sched& S, const Epi& E) {
;     ...
;             PG8_LDA(At, 0, 1); PG8_STAGE(PG8_SB(0, 0), b2, voffB); PG8_STAGE(PG8_SB(0, 1), b2 + hstepB, voffB); PG8_STAGE(PG8_SA(0, 0), a2, voffA);
;             PG8_WAIT_V(8); PG8_WAIT_L(0); PG8_BAR; PG8_MMA(1, 0, At, B0); PG8_MMA(1, 1, At, B1); PG8_BAR; PG8_SCHED;
;             PG8_LDB(B0, 1, 0); PG8_LDB(B1, 1, 1); PG8_SCHED; PG8_LDA(At, 1, 0); PG8_STAGE(PG8_SA(0, 1), a2 + hstepA, voffA);
;             PG8_WAIT_V(8); PG8_WAIT_L(0); PG8_BAR; PG8_MMA(0, 0, At, B0); PG8_MMA(0, 1, At, B1); PG8_BAR; PG8_SCHED;
	s_setprio 1
	s_waitcnt lgkmcnt(0)
	v_mfma_f32_16x16x32_bf16 v[62:65], v[166:169], v[202:205], v[62:65]
	v_mfma_f32_16x16x32_bf16 v[54:57], v[174:177], v[202:205], v[54:57]
	v_mfma_f32_16x16x32_bf16 v[46:49], v[166:169], v[210:213], v[46:49]
	v_mfma_f32_16x16x32_bf16 v[38:41], v[174:177], v[210:213], v[38:41]
	v_mfma_f32_16x16x32_bf16 v[30:33], v[166:169], v[218:221], v[30:33]
	v_mfma_f32_16x16x32_bf16 v[22:25], v[174:177], v[218:221], v[22:25]
	v_mfma_f32_16x16x32_bf16 v[14:17], v[166:169], v[226:229], v[14:17]
	v_mfma_f32_16x16x32_bf16 v[6:9], v[174:177], v[226:229], v[6:9]
	v_mfma_f32_16x16x32_bf16 v[62:65], v[170:173], v[206:209], v[62:65]
	v_mfma_f32_16x16x32_bf16 v[54:57], v[178:181], v[206:209], v[54:57]
	v_mfma_f32_16x16x32_bf16 v[46:49], v[170:173], v[214:217], v[46:49]
	v_mfma_f32_16x16x32_bf16 v[38:41], v[178:181], v[214:217], v[38:41]
	v_mfma_f32_16x16x32_bf16 v[30:33], v[170:173], v[222:225], v[30:33]
	v_mfma_f32_16x16x32_bf16 v[22:25], v[178:181], v[222:225], v[22:25]
	v_mfma_f32_16x16x32_bf16 v[14:17], v[170:173], v[230:233], v[14:17]
	v_mfma_f32_16x16x32_bf16 v[6:9], v[178:181], v[230:233], v[6:9]
	s_setprio 0
	s_setprio 1
	v_mfma_f32_16x16x32_bf16 v[58:61], v[186:189], v[202:205], v[58:61]
	v_mfma_f32_16x16x32_bf16 v[50:53], v[194:197], v[202:205], v[50:53]
	v_mfma_f32_16x16x32_bf16 v[42:45], v[186:189], v[210:213], v[42:45]
	v_mfma_f32_16x16x32_bf16 v[34:37], v[194:197], v[210:213], v[34:37]
	v_mfma_f32_16x16x32_bf16 v[26:29], v[186:189], v[218:221], v[26:29]
	v_mfma_f32_16x16x32_bf16 v[18:21], v[194:197], v[218:221], v[18:21]
	v_mfma_f32_16x16x32_bf16 v[10:13], v[186:189], v[226:229], v[10:13]
	v_mfma_f32_16x16x32_bf16 v[2:5], v[194:197], v[226:229], v[2:5]
	v_mfma_f32_16x16x32_bf16 v[58:61], v[190:193], v[206:209], v[58:61]
	v_mfma_f32_16x16x32_bf16 v[50:53], v[198:201], v[206:209], v[50:53]
	v_mfma_f32_16x16x32_bf16 v[42:45], v[190:193], v[214:217], v[42:45]
	v_mfma_f32_16x16x32_bf16 v[34:37], v[198:201], v[214:217], v[34:37]
	v_mfma_f32_16x16x32_bf16 v[26:29], v[190:193], v[222:225], v[26:29]
	v_mfma_f32_16x16x32_bf16 v[18:21], v[198:201], v[222:225], v[18:21]
	v_mfma_f32_16x16x32_bf16 v[10:13], v[190:193], v[230:233], v[10:13]
	v_mfma_f32_16x16x32_bf16 v[2:5], v[198:201], v[230:233], v[2:5]
	s_setprio 0
	s_barrier
	s_add_i32 s66, 0, 0x18000
	v_add_u32_e32 v165, s66, v156
	s_add_i32 s67, 0, 0x1c000
	ds_read_b128 v[166:169], v165
	ds_read_b128 v[170:173], v165 offset:1024
	ds_read_b128 v[174:177], v165 offset:2048
	ds_read_b128 v[178:181], v165 offset:3072
	v_add_u32_e32 v165, s67, v156
	ds_read_b128 v[186:189], v165
	ds_read_b128 v[190:193], v165 offset:1024
	ds_read_b128 v[194:197], v165 offset:2048
	ds_read_b128 v[198:201], v165 offset:3072
	s_add_u32 s44, s44, 0x40000
	s_addc_u32 s45, s45, 0
	s_mov_b32 m0, s51
	v_lshl_add_u64 v[240:241], s[44:45], 0, v[136:137]
	ds_read_b128 v[202:205], v158 offset:32768
	ds_read_b128 v[206:209], v158 offset:33792
	ds_read_b128 v[210:213], v158 offset:34816
	ds_read_b128 v[214:217], v158 offset:35840
	ds_read_b128 v[218:221], v158 offset:36864
	ds_read_b128 v[222:225], v158 offset:37888
	ds_read_b128 v[226:229], v158 offset:38912
	ds_read_b128 v[230:233], v158 offset:39936
	global_load_lds_dwordx4 v[240:241], off
	v_lshl_add_u64 v[240:241], s[44:45], 0, v[132:133]
	s_mov_b32 m0, s52
	s_nop 0
	global_load_lds_dwordx4 v[240:241], off
	s_waitcnt vmcnt(8)
	s_waitcnt lgkmcnt(0)
	s_barrier
	s_setprio 1
	s_waitcnt lgkmcnt(0)
	v_mfma_f32_16x16x32_bf16 v[126:129], v[166:169], v[202:205], v[126:129]
	v_mfma_f32_16x16x32_bf16 v[118:121], v[174:177], v[202:205], v[118:121]
	v_mfma_f32_16x16x32_bf16 v[110:113], v[166:169], v[210:213], v[110:113]
	v_mfma_f32_16x16x32_bf16 v[102:105], v[174:177], v[210:213], v[102:105]
	v_mfma_f32_16x16x32_bf16 v[94:97], v[166:169], v[218:221], v[94:97]
	v_mfma_f32_16x16x32_bf16 v[86:89], v[174:177], v[218:221], v[86:89]
	v_mfma_f32_16x16x32_bf16 v[78:81], v[166:169], v[226:229], v[78:81]
	v_mfma_f32_16x16x32_bf16 v[70:73], v[174:177], v[226:229], v[70:73]
	v_mfma_f32_16x16x32_bf16 v[126:129], v[170:173], v[206:209], v[126:129]
	v_mfma_f32_16x16x32_bf16 v[118:121], v[178:181], v[206:209], v[118:121]
	v_mfma_f32_16x16x32_bf16 v[110:113], v[170:173], v[214:217], v[110:113]
	v_mfma_f32_16x16x32_bf16 v[102:105], v[178:181], v[214:217], v[102:105]
	v_mfma_f32_16x16x32_bf16 v[94:97], v[170:173], v[222:225], v[94:97]
	v_mfma_f32_16x16x32_bf16 v[86:89], v[178:181], v[222:225], v[86:89]
	v_mfma_f32_16x16x32_bf16 v[78:81], v[170:173], v[230:233], v[78:81]
	v_mfma_f32_16x16x32_bf16 v[70:73], v[178:181], v[230:233], v[70:73]
	s_setprio 0
	s_setprio 1
	v_mfma_f32_16x16x32_bf16 v[122:125], v[186:189], v[202:205], v[122:125]
	v_mfma_f32_16x16x32_bf16 v[114:117], v[194:197], v[202:205], v[114:117]
	v_mfma_f32_16x16x32_bf16 v[106:109], v[186:189], v[210:213], v[106:109]
	v_mfma_f32_16x16x32_bf16 v[98:101], v[194:197], v[210:213], v[98:101]
	v_mfma_f32_16x16x32_bf16 v[90:93], v[186:189], v[218:221], v[90:93]
	v_mfma_f32_16x16x32_bf16 v[82:85], v[194:197], v[218:221], v[82:85]
	v_mfma_f32_16x16x32_bf16 v[74:77], v[186:189], v[226:229], v[74:77]
	v_mfma_f32_16x16x32_bf16 v[66:69], v[194:197], v[226:229], v[66:69]
	v_mfma_f32_16x16x32_bf16 v[122:125], v[190:193], v[206:209], v[122:125]
	v_mfma_f32_16x16x32_bf16 v[114:117], v[198:201], v[206:209], v[114:117]
	v_mfma_f32_16x16x32_bf16 v[106:109], v[190:193], v[214:217], v[106:109]
	v_mfma_f32_16x16x32_bf16 v[98:101], v[198:201], v[214:217], v[98:101]
	v_mfma_f32_16x16x32_bf16 v[90:93], v[190:193], v[222:225], v[90:93]
	v_mfma_f32_16x16x32_bf16 v[82:85], v[198:201], v[222:225], v[82:85]
	v_mfma_f32_16x16x32_bf16 v[74:77], v[190:193], v[230:233], v[74:77]
	v_mfma_f32_16x16x32_bf16 v[66:69], v[198:201], v[230:233], v[66:69]
	s_setprio 0
	s_barrier
; #define PG8_STAGE(bufoff, gbase, voff) do { _Pragma("unroll") for (int _i = 0; _i < 2; ++_i) \
;         __builtin_amdgcn_global_load_lds((const unsigned*)((const char*)(gbase) + (voff)[_i]), (LAS unsigned*)(lds + (bufoff) + ldsw + _i * 8192), 16, 0, 0); } while (0)
; #define PG8_LDA(dst, b, h) do { _Pragma("unroll") for (int m = 0; m < 4; ++m) _Pragma("unroll") for (int k = 0; k < 2; ++k) dst[m][k] = *(const LAS bf16x8*)(lds + PG8_SA(b, h) + aoff + m * 2048 + k * 1024); } while (0)
; #define PG8_LDB(dst, b, h) do { _Pragma("unroll") for (int n = 0; n < 2; ++n) _Pragma("unroll") for (int k = 0; k < 2; ++k) dst[n][k] = *(const LAS bf16x8*)(lds + PG8_SB(b, h) + boff + n * 2048 + k * 1024); } while (0)
; #define PG8_MMA(ai, bj, At, Bt) do { __builtin_amdgcn_s_setprio(1); _Pragma("unroll") for (int m = 0; m < 4; ++m) _Pragma("unroll") for (int n = 0; n < 2; ++n) _Pragma("unroll") for (int k = 0; k < 2; ++k) \
;         acc[ai][bj][m][n] = __builtin_amdgcn_mfma_f32_16x16x32_bf16(Bt[n][k], At[m][k], acc[ai][bj][m][n], 0, 0, 0); __builtin_amdgcn_s_setprio(0); } while (0)
; #define PG8_WAIT_V(n) asm volatile("s_waitcnt vmcnt(" #n ")" ::: "memory")
; #define PG8_WAIT_L(n) asm volatile("s_waitcnt lgkmcnt(" #n ")" ::: "memory")
; #define PG8_BAR __builtin_amdgcn_s_barrier()
; #define PG8_SCHED __builtin_amdgcn_sched_barrier(0)
; template <class Epi, class Sched>
; DI void gemm_phase(LAS unsigned char* lds, const Gemm g, const Sched& S, const Epi& E) {
;     ...
;             PG8_LDB(B0, 1, 0); PG8_LDB(B1, 1, 1); PG8_SCHED; PG8_LDA(At, 1, 0); PG8_STAGE(PG8_SA(0, 1), a2 + hstepA, voffA);
;             PG8_WAIT_V(8); PG8_WAIT_L(0); PG8_BAR; PG8_MMA(0, 0, At, B0); PG8_MMA(0, 1, At, B1); PG8_BAR; PG8_SCHED;
;             PG8_LDA(At, 1, 1); PG8_STAGE(PG8_SB(1, 0), b3, voffB); PG8_STAGE(PG8_SB(1, 1), b3 + hstepB, voffB); PG8_STAGE(PG8_SA(1, 0), a3, voffA);
;             PG8_WAIT_V(8); PG8_WAIT_L(0); PG8_BAR; PG8_MMA(1, 0, At, B0); PG8_MMA(1, 1, At, B1); PG8_BAR; PG8_SCHED;
;         }
;         if (wr == 0) PG8_BAR;
	s_add_i32 s44, s66, s46
	v_lshl_add_u64 v[182:183], v[182:183], 0, s[16:17]
	s_mov_b32 m0, s44
	ds_read_b128 v[202:205], v158 offset:49152
	ds_read_b128 v[206:209], v158 offset:50176
	ds_read_b128 v[210:213], v158 offset:51200
	ds_read_b128 v[214:217], v158 offset:52224
	ds_read_b128 v[218:221], v158 offset:53248
	ds_read_b128 v[222:225], v158 offset:54272
	ds_read_b128 v[226:229], v158 offset:55296
	ds_read_b128 v[230:233], v158 offset:56320
	global_load_lds_dwordx4 v[182:183], off
	s_add_i32 m0, s44, 0x2000
	s_add_u32 s42, s42, 0x40080
	v_lshl_add_u64 v[182:183], v[234:235], 0, s[16:17]
	s_addc_u32 s43, s43, 0
	s_add_i32 s44, s67, s46
	global_load_lds_dwordx4 v[182:183], off
	v_lshl_add_u64 v[182:183], s[42:43], 0, v[134:135]
	s_mov_b32 m0, s44
	s_nop 0
	global_load_lds_dwordx4 v[182:183], off
	v_lshl_add_u64 v[182:183], s[42:43], 0, v[130:131]
	s_add_i32 m0, s44, 0x2000
	s_nop 0
	global_load_lds_dwordx4 v[182:183], off
	v_lshl_add_u64 v[182:183], v[236:237], 0, s[16:17]
	s_mov_b32 m0, s54
	s_nop 0
	global_load_lds_dwordx4 v[182:183], off
	v_lshl_add_u64 v[182:183], v[238:239], 0, s[16:17]
	s_mov_b32 m0, s55
	s_nop 0
	global_load_lds_dwordx4 v[182:183], off
	s_waitcnt vmcnt(8)
	s_waitcnt lgkmcnt(0)
	s_barrier
	s_setprio 1
	s_waitcnt lgkmcnt(0)
	v_mfma_f32_16x16x32_bf16 v[62:65], v[166:169], v[202:205], v[62:65]
	v_mfma_f32_16x16x32_bf16 v[54:57], v[174:177], v[202:205], v[54:57]
	v_mfma_f32_16x16x32_bf16 v[46:49], v[166:169], v[210:213], v[46:49]
	v_mfma_f32_16x16x32_bf16 v[38:41], v[174:177], v[210:213], v[38:41]
	v_mfma_f32_16x16x32_bf16 v[30:33], v[166:169], v[218:221], v[30:33]
	v_mfma_f32_16x16x32_bf16 v[22:25], v[174:177], v[218:221], v[22:25]
	v_mfma_f32_16x16x32_bf16 v[14:17], v[166:169], v[226:229], v[14:17]
	v_mfma_f32_16x16x32_bf16 v[6:9], v[174:177], v[226:229], v[6:9]
	v_mfma_f32_16x16x32_bf16 v[62:65], v[170:173], v[206:209], v[62:65]
	v_mfma_f32_16x16x32_bf16 v[54:57], v[178:181], v[206:209], v[54:57]
	v_mfma_f32_16x16x32_bf16 v[46:49], v[170:173], v[214:217], v[46:49]
	v_mfma_f32_16x16x32_bf16 v[38:41], v[178:181], v[214:217], v[38:41]
	v_mfma_f32_16x16x32_bf16 v[30:33], v[170:173], v[222:225], v[30:33]
	v_mfma_f32_16x16x32_bf16 v[22:25], v[178:181], v[222:225], v[22:25]
	v_mfma_f32_16x16x32_bf16 v[14:17], v[170:173], v[230:233], v[14:17]
	v_mfma_f32_16x16x32_bf16 v[6:9], v[178:181], v[230:233], v[6:9]
	s_setprio 0
	s_setprio 1
	v_mfma_f32_16x16x32_bf16 v[58:61], v[186:189], v[202:205], v[58:61]
	v_mfma_f32_16x16x32_bf16 v[50:53], v[194:197], v[202:205], v[50:53]
	v_mfma_f32_16x16x32_bf16 v[42:45], v[186:189], v[210:213], v[42:45]
	v_mfma_f32_16x16x32_bf16 v[34:37], v[194:197], v[210:213], v[34:37]
	v_mfma_f32_16x16x32_bf16 v[26:29], v[186:189], v[218:221], v[26:29]
	v_mfma_f32_16x16x32_bf16 v[18:21], v[194:197], v[218:221], v[18:21]
	v_mfma_f32_16x16x32_bf16 v[10:13], v[186:189], v[226:229], v[10:13]
	v_mfma_f32_16x16x32_bf16 v[2:5], v[194:197], v[226:229], v[2:5]
	v_mfma_f32_16x16x32_bf16 v[58:61], v[190:193], v[206:209], v[58:61]
	v_mfma_f32_16x16x32_bf16 v[50:53], v[198:201], v[206:209], v[50:53]
	v_mfma_f32_16x16x32_bf16 v[42:45], v[190:193], v[214:217], v[42:45]
	v_mfma_f32_16x16x32_bf16 v[34:37], v[198:201], v[214:217], v[34:37]
	v_mfma_f32_16x16x32_bf16 v[26:29], v[190:193], v[222:225], v[26:29]
	v_mfma_f32_16x16x32_bf16 v[18:21], v[198:201], v[222:225], v[18:21]
	v_mfma_f32_16x16x32_bf16 v[10:13], v[190:193], v[230:233], v[10:13]
	v_mfma_f32_16x16x32_bf16 v[2:5], v[198:201], v[230:233], v[2:5]
	s_setprio 0
	s_barrier
	s_add_i32 s65, s65, 2
	s_add_u32 s40, s40, 0x100
	s_addc_u32 s41, s41, 0
	s_add_u32 s63, s63, 0x100
	s_addc_u32 s64, s64, 0
	s_cmp_gt_u32 s65, 13
	s_cbranch_scc0 .LBB0_1234
	s_and_b64 vcc, exec, s[18:19]
	s_cbranch_vccz .LBB0_1237
	s_barrier

; #define PG8_STAGE(bufoff, gbase, voff) do { _Pragma("unroll") for (int _i = 0; _i < 2; ++_i) \
;         __builtin_amdgcn_global_load_lds((const unsigned*)((const char*)(gbase) + (voff)[_i]), (LAS unsigned*)(lds + (bufoff) + ldsw + _i * 8192), 16, 0, 0); } while (0)
; #define PG8_LDA(dst, b, h) do { _Pragma("unroll") for (int m = 0; m < 4; ++m) _Pragma("unroll") for (int k = 0; k < 2; ++k) dst[m][k] = *(const LAS bf16x8*)(lds + PG8_SA(b, h) + aoff + m * 2048 + k * 1024); } while (0)
; #define PG8_LDB(dst, b, h) do { _Pragma("unroll") for (int n = 0; n < 2; ++n) _Pragma("unroll") for (int k = 0; k < 2; ++k) dst[n][k] = *(const LAS bf16x8*)(lds + PG8_SB(b, h) + boff + n * 2048 + k * 1024); } while (0)
; #define PG8_WAIT_V(n) asm volatile("s_waitcnt vmcnt(" #n ")" ::: "memory")
; #define PG8_WAIT_L(n) asm volatile("s_waitcnt lgkmcnt(" #n ")" ::: "memory")
; #define PG8_BAR __builtin_amdgcn_s_barrier()
; #define PG8_SCHED __builtin_amdgcn_sched_barrier(0)
; template <class Epi, class Sched>
; DI void gemm_phase(LAS unsigned char* lds, const Gemm g, const Sched& S, const Epi& E) {
;     ...
;         for (int t = 0; t < nt; t += 2) {
;             const bool last = (t == nt - 2);
;             const char* a1 = cA + (size_t)(t + 1) * kstep;
;             const char* a2 = last ? nA : cA + (size_t)(t + 2) * kstep; const char* b2 = last ? nB : cB + (size_t)(t + 2) * kstep;
;             const char* a3 = a2 + kstep; const char* b3 = b2 + kstep;
;             PG8_LDB(B0, 0, 0); PG8_LDB(B1, 0, 1); PG8_SCHED; PG8_LDA(At, 0, 0); PG8_STAGE(PG8_SA(1, 1), a1 + hstepA, voffA);
;             PG8_WAIT_V(8); PG8_WAIT_L(0); PG8_BAR; PG8_MMA(0, 0, At, B0); PG8_MMA(0, 1, At, B1); PG8_BAR; PG8_SCHED;
;             PG8_LDA(At, 0, 1); PG8_STAGE(PG8_SB(0, 0), b2, voffB); PG8_STAGE(PG8_SB(0, 1), b2 + hstepB, voffB); PG8_STAGE(PG8_SA(0, 0), a2, voffA);
;             PG8_WAIT_V(8); PG8_WAIT_L(0); PG8_BAR; PG8_MMA(1, 0, At, B0); PG8_MMA(1, 1, At, B1); PG8_BAR; PG8_SCHED;
;     ...
;         if (!(Epi::CHAIN && cur.src == 0)) {
; #pragma unroll
;             for (int a = 0; a < 2; ++a)
; #pragma unroll
;                 for (int b = 0; b < 2; ++b)
; #pragma unroll
;                     for (int m = 0; m < 4; ++m)
; #pragma unroll
;                         for (int n = 0; n < 2; ++n) acc[a][b][m][n] = (f32x4){0.f, 0.f, 0.f, 0.f};
;         }
.LBB0_1330:
	s_add_u32 s16, s16, 0xb0080
	s_addc_u32 s17, s17, 0
	s_add_u32 s45, s18, 0x100
	v_mov_b32_e32 v0, 0
	s_addc_u32 s46, s19, 0
	s_mov_b32 s47, -2
	v_mov_b32_e32 v1, v0
	v_mov_b32_e32 v2, v0
	v_mov_b32_e32 v3, v0
	v_mov_b32_e32 v4, v0
	v_mov_b32_e32 v5, v0
	v_mov_b32_e32 v6, v0
	v_mov_b32_e32 v7, v0
	v_mov_b32_e32 v16, v0
	v_mov_b32_e32 v17, v0
	v_mov_b32_e32 v18, v0
	v_mov_b32_e32 v19, v0
	v_mov_b32_e32 v20, v0
	v_mov_b32_e32 v21, v0
	v_mov_b32_e32 v22, v0
	v_mov_b32_e32 v23, v0
	v_mov_b32_e32 v32, v0
	v_mov_b32_e32 v33, v0
	v_mov_b32_e32 v34, v0
	v_mov_b32_e32 v35, v0
	v_mov_b32_e32 v36, v0
	v_mov_b32_e32 v37, v0
	v_mov_b32_e32 v38, v0
	v_mov_b32_e32 v39, v0
	v_mov_b32_e32 v48, v0
	v_mov_b32_e32 v49, v0
	v_mov_b32_e32 v50, v0
	v_mov_b32_e32 v51, v0
	v_mov_b32_e32 v52, v0
	v_mov_b32_e32 v53, v0
	v_mov_b32_e32 v54, v0
	v_mov_b32_e32 v55, v0
	v_mov_b32_e32 v8, v0
	v_mov_b32_e32 v9, v0
	v_mov_b32_e32 v10, v0
	v_mov_b32_e32 v11, v0
	v_mov_b32_e32 v12, v0
	v_mov_b32_e32 v13, v0
	v_mov_b32_e32 v14, v0
	v_mov_b32_e32 v15, v0
	v_mov_b32_e32 v24, v0
	v_mov_b32_e32 v25, v0
	v_mov_b32_e32 v26, v0
	v_mov_b32_e32 v27, v0
	v_mov_b32_e32 v28, v0
	v_mov_b32_e32 v29, v0
	v_mov_b32_e32 v30, v0
	v_mov_b32_e32 v31, v0
	v_mov_b32_e32 v40, v0
	v_mov_b32_e32 v41, v0
	v_mov_b32_e32 v42, v0
	v_mov_b32_e32 v43, v0
	v_mov_b32_e32 v44, v0
	v_mov_b32_e32 v45, v0
	v_mov_b32_e32 v46, v0
	v_mov_b32_e32 v47, v0
	v_mov_b32_e32 v56, v0
	v_mov_b32_e32 v57, v0
	v_mov_b32_e32 v58, v0
	v_mov_b32_e32 v59, v0
	v_mov_b32_e32 v60, v0
	v_mov_b32_e32 v61, v0
	v_mov_b32_e32 v62, v0
	v_mov_b32_e32 v63, v0
	v_mov_b32_e32 v64, v0
	v_mov_b32_e32 v65, v0
	v_mov_b32_e32 v66, v0
	v_mov_b32_e32 v67, v0
	v_mov_b32_e32 v68, v0
	v_mov_b32_e32 v69, v0
	v_mov_b32_e32 v70, v0
	v_mov_b32_e32 v71, v0
	v_mov_b32_e32 v80, v0
	v_mov_b32_e32 v81, v0
	v_mov_b32_e32 v82, v0
	v_mov_b32_e32 v83, v0
	v_mov_b32_e32 v84, v0
	v_mov_b32_e32 v85, v0
	v_mov_b32_e32 v86, v0
	v_mov_b32_e32 v87, v0
	v_mov_b32_e32 v96, v0
	v_mov_b32_e32 v97, v0
	v_mov_b32_e32 v98, v0
	v_mov_b32_e32 v99, v0
	v_mov_b32_e32 v100, v0
	v_mov_b32_e32 v101, v0
	v_mov_b32_e32 v102, v0
	v_mov_b32_e32 v103, v0
	v_mov_b32_e32 v112, v0
	v_mov_b32_e32 v113, v0
	v_mov_b32_e32 v114, v0
	v_mov_b32_e32 v115, v0
	v_mov_b32_e32 v116, v0
	v_mov_b32_e32 v117, v0
	v_mov_b32_e32 v118, v0
	v_mov_b32_e32 v119, v0
	v_mov_b32_e32 v72, v0
	v_mov_b32_e32 v73, v0
	v_mov_b32_e32 v74, v0
	v_mov_b32_e32 v75, v0
	v_mov_b32_e32 v76, v0
	v_mov_b32_e32 v77, v0
	v_mov_b32_e32 v78, v0
	v_mov_b32_e32 v79, v0
	v_mov_b32_e32 v88, v0
	v_mov_b32_e32 v89, v0
	v_mov_b32_e32 v90, v0
	v_mov_b32_e32 v91, v0
	v_mov_b32_e32 v92, v0
	v_mov_b32_e32 v93, v0
	v_mov_b32_e32 v94, v0
	v_mov_b32_e32 v95, v0
	v_mov_b32_e32 v104, v0
	v_mov_b32_e32 v105, v0
	v_mov_b32_e32 v106, v0
	v_mov_b32_e32 v107, v0
	v_mov_b32_e32 v108, v0
	v_mov_b32_e32 v109, v0
	v_mov_b32_e32 v110, v0
	v_mov_b32_e32 v111, v0
	v_mov_b32_e32 v120, v0
	v_mov_b32_e32 v121, v0
	v_mov_b32_e32 v122, v0
	v_mov_b32_e32 v123, v0
	v_mov_b32_e32 v124, v0
	v_mov_b32_e32 v125, v0
	v_mov_b32_e32 v126, v0
	v_mov_b32_e32 v127, v0
.LBB0_1331:
	ds_read_b128 v[144:147], v151
	ds_read_b128 v[154:157], v151 offset:1024
	ds_read_b128 v[158:161], v151 offset:2048
	ds_read_b128 v[162:165], v151 offset:3072
	ds_read_b128 v[166:169], v152
	ds_read_b128 v[170:173], v152 offset:1024
	ds_read_b128 v[174:177], v152 offset:2048
	ds_read_b128 v[178:181], v152 offset:3072
	s_add_u32 s18, s16, 0xfff50080
	s_addc_u32 s19, s17, -1
	s_cmp_eq_u32 s47, 40
	s_cselect_b32 s21, s5, s19
	s_cselect_b32 s20, s4, s18
	s_cselect_b32 s19, s15, s46
	s_cselect_b32 s18, s14, s45
	v_lshl_add_u64 v[214:215], s[16:17], 0, v[136:137]
	s_add_i32 m0, s28, 0xc000
	ds_read_b128 v[182:185], v153
	ds_read_b128 v[186:189], v153 offset:1024
	ds_read_b128 v[190:193], v153 offset:2048
	ds_read_b128 v[194:197], v153 offset:3072
	ds_read_b128 v[198:201], v153 offset:4096
	ds_read_b128 v[202:205], v153 offset:5120
	ds_read_b128 v[206:209], v153 offset:6144
	ds_read_b128 v[210:213], v153 offset:7168
	global_load_lds_dwordx4 v[214:215], off
	v_lshl_add_u64 v[214:215], s[16:17], 0, v[138:139]
	s_add_i32 m0, s28, 0xe000
	s_nop 0
	global_load_lds_dwordx4 v[214:215], off
	s_waitcnt vmcnt(8)
	s_waitcnt lgkmcnt(0)
	s_barrier
	s_setprio 1
	s_waitcnt lgkmcnt(0)
	v_mfma_f32_16x16x32_bf16 v[124:127], v[144:147], v[182:185], v[124:127]
	v_mfma_f32_16x16x32_bf16 v[120:123], v[158:161], v[182:185], v[120:123]
	v_mfma_f32_16x16x32_bf16 v[108:111], v[144:147], v[190:193], v[108:111]
	v_mfma_f32_16x16x32_bf16 v[104:107], v[158:161], v[190:193], v[104:107]
	v_mfma_f32_16x16x32_bf16 v[92:95], v[144:147], v[198:201], v[92:95]
	v_mfma_f32_16x16x32_bf16 v[88:91], v[158:161], v[198:201], v[88:91]
	v_mfma_f32_16x16x32_bf16 v[76:79], v[144:147], v[206:209], v[76:79]
	v_mfma_f32_16x16x32_bf16 v[72:75], v[158:161], v[206:209], v[72:75]
	v_mfma_f32_16x16x32_bf16 v[124:127], v[154:157], v[186:189], v[124:127]
	v_mfma_f32_16x16x32_bf16 v[120:123], v[162:165], v[186:189], v[120:123]
	v_mfma_f32_16x16x32_bf16 v[108:111], v[154:157], v[194:197], v[108:111]
	v_mfma_f32_16x16x32_bf16 v[104:107], v[162:165], v[194:197], v[104:107]
	v_mfma_f32_16x16x32_bf16 v[92:95], v[154:157], v[202:205], v[92:95]
	v_mfma_f32_16x16x32_bf16 v[88:91], v[162:165], v[202:205], v[88:91]
	v_mfma_f32_16x16x32_bf16 v[76:79], v[154:157], v[210:213], v[76:79]
	v_mfma_f32_16x16x32_bf16 v[72:75], v[162:165], v[210:213], v[72:75]
	s_setprio 0
	s_setprio 1
	v_mfma_f32_16x16x32_bf16 v[116:119], v[166:169], v[182:185], v[116:119]
	v_mfma_f32_16x16x32_bf16 v[112:115], v[174:177], v[182:185], v[112:115]
	v_mfma_f32_16x16x32_bf16 v[100:103], v[166:169], v[190:193], v[100:103]
	v_mfma_f32_16x16x32_bf16 v[96:99], v[174:177], v[190:193], v[96:99]
	v_mfma_f32_16x16x32_bf16 v[84:87], v[166:169], v[198:201], v[84:87]
	v_mfma_f32_16x16x32_bf16 v[80:83], v[174:177], v[198:201], v[80:83]
	v_mfma_f32_16x16x32_bf16 v[68:71], v[166:169], v[206:209], v[68:71]
	v_mfma_f32_16x16x32_bf16 v[64:67], v[174:177], v[206:209], v[64:67]
	v_mfma_f32_16x16x32_bf16 v[116:119], v[170:173], v[186:189], v[116:119]
	v_mfma_f32_16x16x32_bf16 v[112:115], v[178:181], v[186:189], v[112:115]
	v_mfma_f32_16x16x32_bf16 v[100:103], v[170:173], v[194:197], v[100:103]
	v_mfma_f32_16x16x32_bf16 v[96:99], v[178:181], v[194:197], v[96:99]
	v_mfma_f32_16x16x32_bf16 v[84:87], v[170:173], v[202:205], v[84:87]
	v_mfma_f32_16x16x32_bf16 v[80:83], v[178:181], v[202:205], v[80:83]
	v_mfma_f32_16x16x32_bf16 v[68:71], v[170:173], v[210:213], v[68:71]
	v_mfma_f32_16x16x32_bf16 v[64:67], v[178:181], v[210:213], v[64:67]
	s_setprio 0
	s_barrier
; #define PG8_STAGE(bufoff, gbase, voff) do { _Pragma("unroll") for (int _i = 0; _i < 2; ++_i) \
;         __builtin_amdgcn_global_load_lds((const unsigned*)((const char*)(gbase) + (voff)[_i]), (LAS unsigned*)(lds + (bufoff) + ldsw + _i * 8192), 16, 0, 0); } while (0)
; #define PG8_LDA(dst, b, h) do { _Pragma("unroll") for (int m = 0; m < 4; ++m) _Pragma("unroll") for (int k = 0; k < 2; ++k) dst[m][k] = *(const LAS bf16x8*)(lds + PG8_SA(b, h) + aoff + m * 2048 + k * 1024); } while (0)
; #define PG8_LDB(dst, b, h) do { _Pragma("unroll") for (int n = 0; n < 2; ++n) _Pragma("unroll") for (int k = 0; k < 2; ++k) dst[n][k] = *(const LAS bf16x8*)(lds + PG8_SB(b, h) + boff + n * 2048 + k * 1024); } while (0)
; #define PG8_MMA(ai, bj, At, Bt) do { __builtin_amdgcn_s_setprio(1); _Pragma("unroll") for (int m = 0; m < 4; ++m) _Pragma("unroll") for (int n = 0; n < 2; ++n) _Pragma("unroll") for (int k = 0; k < 2; ++k) \
;         acc[ai][bj][m][n] = __builtin_amdgcn_mfma_f32_16x16x32_bf16(Bt[n][k], At[m][k], acc[ai][bj][m][n], 0, 0, 0); __builtin_amdgcn_s_setprio(0); } while (0)
; #define PG8_WAIT_V(n) asm volatile("s_waitcnt vmcnt(" #n ")" ::: "memory")
; #define PG8_WAIT_L(n) asm volatile("s_waitcnt lgkmcnt(" #n ")" ::: "memory")
; #define PG8_BAR __builtin_amdgcn_s_barrier()
; #define PG8_SCHED __builtin_amdgcn_sched_barrier(0)
; template <class Epi, class Sched>
; DI void gemm_phase(LAS unsigned char* lds, const Gemm g, const Sched& S, const Epi& E) {
;     ...
;             PG8_LDA(At, 0, 1); PG8_STAGE(PG8_SB(0, 0), b2, voffB); PG8_STAGE(PG8_SB(0, 1), b2 + hstepB, voffB); PG8_STAGE(PG8_SA(0, 0), a2, voffA);
;             PG8_WAIT_V(8); PG8_WAIT_L(0); PG8_BAR; PG8_MMA(1, 0, At, B0); PG8_MMA(1, 1, At, B1); PG8_BAR; PG8_SCHED;
;             PG8_LDB(B0, 1, 0); PG8_LDB(B1, 1, 1); PG8_SCHED; PG8_LDA(At, 1, 0); PG8_STAGE(PG8_SA(0, 1), a2 + hstepA, voffA);
;             PG8_WAIT_V(8); PG8_WAIT_L(0); PG8_BAR; PG8_MMA(0, 0, At, B0); PG8_MMA(0, 1, At, B1); PG8_BAR; PG8_SCHED;
	s_add_i32 s48, s39, s27
	v_lshl_add_u64 v[214:215], s[18:19], 0, v[130:131]
	s_mov_b32 m0, s48
	ds_read_b128 v[182:185], v153 offset:16384
	ds_read_b128 v[186:189], v153 offset:17408
	ds_read_b128 v[190:193], v153 offset:18432
	ds_read_b128 v[194:197], v153 offset:19456
	ds_read_b128 v[198:201], v153 offset:20480
	ds_read_b128 v[202:205], v153 offset:21504
	ds_read_b128 v[206:209], v153 offset:22528
	ds_read_b128 v[210:213], v153 offset:23552
	global_load_lds_dwordx4 v[214:215], off
	s_add_i32 m0, s48, 0x2000
	s_add_u32 s48, s18, 0xb0000
	v_lshl_add_u64 v[216:217], s[18:19], 0, v[134:135]
	s_addc_u32 s49, s19, 0
	s_add_i32 s50, s40, s27
	global_load_lds_dwordx4 v[216:217], off
	v_lshl_add_u64 v[218:219], s[48:49], 0, v[130:131]
	s_mov_b32 m0, s50
	v_lshl_add_u64 v[220:221], s[20:21], 0, v[132:133]
	global_load_lds_dwordx4 v[218:219], off
	v_lshl_add_u64 v[218:219], s[48:49], 0, v[134:135]
	s_add_i32 m0, s50, 0x2000
	s_nop 0
	global_load_lds_dwordx4 v[218:219], off
	v_lshl_add_u64 v[218:219], s[20:21], 0, v[128:129]
	s_mov_b32 m0, s28
	s_nop 0
	global_load_lds_dwordx4 v[218:219], off
	s_mov_b32 m0, s29
	s_nop 0
	global_load_lds_dwordx4 v[220:221], off
	s_waitcnt vmcnt(8)
	s_waitcnt lgkmcnt(0)
	s_barrier
	s_setprio 1
	s_waitcnt lgkmcnt(0)
	v_mfma_f32_16x16x32_bf16 v[60:63], v[144:147], v[182:185], v[60:63]
	v_mfma_f32_16x16x32_bf16 v[56:59], v[158:161], v[182:185], v[56:59]
	v_mfma_f32_16x16x32_bf16 v[44:47], v[144:147], v[190:193], v[44:47]
	v_mfma_f32_16x16x32_bf16 v[40:43], v[158:161], v[190:193], v[40:43]
	v_mfma_f32_16x16x32_bf16 v[28:31], v[144:147], v[198:201], v[28:31]
	v_mfma_f32_16x16x32_bf16 v[24:27], v[158:161], v[198:201], v[24:27]
	v_mfma_f32_16x16x32_bf16 v[12:15], v[144:147], v[206:209], v[12:15]
	v_mfma_f32_16x16x32_bf16 v[8:11], v[158:161], v[206:209], v[8:11]
	v_mfma_f32_16x16x32_bf16 v[60:63], v[154:157], v[186:189], v[60:63]
	v_mfma_f32_16x16x32_bf16 v[56:59], v[162:165], v[186:189], v[56:59]
	v_mfma_f32_16x16x32_bf16 v[44:47], v[154:157], v[194:197], v[44:47]
	v_mfma_f32_16x16x32_bf16 v[40:43], v[162:165], v[194:197], v[40:43]
	v_mfma_f32_16x16x32_bf16 v[28:31], v[154:157], v[202:205], v[28:31]
	v_mfma_f32_16x16x32_bf16 v[24:27], v[162:165], v[202:205], v[24:27]
	v_mfma_f32_16x16x32_bf16 v[12:15], v[154:157], v[210:213], v[12:15]
	v_mfma_f32_16x16x32_bf16 v[8:11], v[162:165], v[210:213], v[8:11]
	s_setprio 0
	s_setprio 1
	v_mfma_f32_16x16x32_bf16 v[52:55], v[166:169], v[182:185], v[52:55]
	v_mfma_f32_16x16x32_bf16 v[48:51], v[174:177], v[182:185], v[48:51]
	v_mfma_f32_16x16x32_bf16 v[36:39], v[166:169], v[190:193], v[36:39]
	v_mfma_f32_16x16x32_bf16 v[32:35], v[174:177], v[190:193], v[32:35]
	v_mfma_f32_16x16x32_bf16 v[20:23], v[166:169], v[198:201], v[20:23]
	v_mfma_f32_16x16x32_bf16 v[16:19], v[174:177], v[198:201], v[16:19]
	v_mfma_f32_16x16x32_bf16 v[4:7], v[166:169], v[206:209], v[4:7]
	v_mfma_f32_16x16x32_bf16 v[0:3], v[174:177], v[206:209], v[0:3]
	v_mfma_f32_16x16x32_bf16 v[52:55], v[170:173], v[186:189], v[52:55]
	v_mfma_f32_16x16x32_bf16 v[48:51], v[178:181], v[186:189], v[48:51]
	v_mfma_f32_16x16x32_bf16 v[36:39], v[170:173], v[194:197], v[36:39]
	v_mfma_f32_16x16x32_bf16 v[32:35], v[178:181], v[194:197], v[32:35]
	v_mfma_f32_16x16x32_bf16 v[20:23], v[170:173], v[202:205], v[20:23]
	v_mfma_f32_16x16x32_bf16 v[16:19], v[178:181], v[202:205], v[16:19]
	v_mfma_f32_16x16x32_bf16 v[4:7], v[170:173], v[210:213], v[4:7]
	v_mfma_f32_16x16x32_bf16 v[0:3], v[178:181], v[210:213], v[0:3]
	s_setprio 0
	s_barrier
	s_add_i32 s48, 0, 0x18000
	s_add_i32 s49, 0, 0x1c000
	v_add_u32_e32 v162, s48, v149
	v_add_u32_e32 v178, s49, v149
	ds_read_b128 v[144:147], v162
	ds_read_b128 v[154:157], v162 offset:1024
	ds_read_b128 v[158:161], v162 offset:2048
	ds_read_b128 v[162:165], v162 offset:3072
	ds_read_b128 v[166:169], v178
	ds_read_b128 v[170:173], v178 offset:1024
	ds_read_b128 v[174:177], v178 offset:2048
	ds_read_b128 v[178:181], v178 offset:3072
	s_add_u32 s20, s20, 0xb0000
	s_addc_u32 s21, s21, 0
	s_mov_b32 m0, s33
	v_lshl_add_u64 v[222:223], s[20:21], 0, v[128:129]
	ds_read_b128 v[182:185], v153 offset:32768
	ds_read_b128 v[186:189], v153 offset:33792
	ds_read_b128 v[190:193], v153 offset:34816
	ds_read_b128 v[194:197], v153 offset:35840
	ds_read_b128 v[198:201], v153 offset:36864
	ds_read_b128 v[202:205], v153 offset:37888
	ds_read_b128 v[206:209], v153 offset:38912
	ds_read_b128 v[210:213], v153 offset:39936
	global_load_lds_dwordx4 v[222:223], off
	v_lshl_add_u64 v[222:223], s[20:21], 0, v[132:133]
	s_mov_b32 m0, s34
	s_nop 0
	global_load_lds_dwordx4 v[222:223], off
	s_waitcnt vmcnt(8)
	s_waitcnt lgkmcnt(0)
	s_barrier
; #define PG8_STAGE(bufoff, gbase, voff) do { _Pragma("unroll") for (int _i = 0; _i < 2; ++_i) \
;         __builtin_amdgcn_global_load_lds((const unsigned*)((const char*)(gbase) + (voff)[_i]), (LAS unsigned*)(lds + (bufoff) + ldsw + _i * 8192), 16, 0, 0); } while (0)
; #define PG8_LDA(dst, b, h) do { _Pragma("unroll") for (int m = 0; m < 4; ++m) _Pragma("unroll") for (int k = 0; k < 2; ++k) dst[m][k] = *(const LAS bf16x8*)(lds + PG8_SA(b, h) + aoff + m * 2048 + k * 1024); } while (0)
; #define PG8_LDB(dst, b, h) do { _Pragma("unroll") for (int n = 0; n < 2; ++n) _Pragma("unroll") for (int k = 0; k < 2; ++k) dst[n][k] = *(const LAS bf16x8*)(lds + PG8_SB(b, h) + boff + n * 2048 + k * 1024); } while (0)
; #define PG8_MMA(ai, bj, At, Bt) do { __builtin_amdgcn_s_setprio(1); _Pragma("unroll") for (int m = 0; m < 4; ++m) _Pragma("unroll") for (int n = 0; n < 2; ++n) _Pragma("unroll") for (int k = 0; k < 2; ++k) \
;         acc[ai][bj][m][n] = __builtin_amdgcn_mfma_f32_16x16x32_bf16(Bt[n][k], At[m][k], acc[ai][bj][m][n], 0, 0, 0); __builtin_amdgcn_s_setprio(0); } while (0)
; #define PG8_WAIT_V(n) asm volatile("s_waitcnt vmcnt(" #n ")" ::: "memory")
; #define PG8_WAIT_L(n) asm volatile("s_waitcnt lgkmcnt(" #n ")" ::: "memory")
; #define PG8_BAR __builtin_amdgcn_s_barrier()
; #define PG8_SCHED __builtin_amdgcn_sched_barrier(0)
; template <class Epi, class Sched>
; DI void gemm_phase(LAS unsigned char* lds, const Gemm g, const Sched& S, const Epi& E) {
;     ...
;             PG8_LDB(B0, 1, 0); PG8_LDB(B1, 1, 1); PG8_SCHED; PG8_LDA(At, 1, 0); PG8_STAGE(PG8_SA(0, 1), a2 + hstepA, voffA);
;             PG8_WAIT_V(8); PG8_WAIT_L(0); PG8_BAR; PG8_MMA(0, 0, At, B0); PG8_MMA(0, 1, At, B1); PG8_BAR; PG8_SCHED;
;             PG8_LDA(At, 1, 1); PG8_STAGE(PG8_SB(1, 0), b3, voffB); PG8_STAGE(PG8_SB(1, 1), b3 + hstepB, voffB); PG8_STAGE(PG8_SA(1, 0), a3, voffA);
;             PG8_WAIT_V(8); PG8_WAIT_L(0); PG8_BAR; PG8_MMA(1, 0, At, B0); PG8_MMA(1, 1, At, B1); PG8_BAR; PG8_SCHED;
;         }
;         if (wr == 0) PG8_BAR;
	s_setprio 1
	s_waitcnt lgkmcnt(0)
	v_mfma_f32_16x16x32_bf16 v[124:127], v[144:147], v[182:185], v[124:127]
	v_mfma_f32_16x16x32_bf16 v[120:123], v[158:161], v[182:185], v[120:123]
	v_mfma_f32_16x16x32_bf16 v[108:111], v[144:147], v[190:193], v[108:111]
	v_mfma_f32_16x16x32_bf16 v[104:107], v[158:161], v[190:193], v[104:107]
	v_mfma_f32_16x16x32_bf16 v[92:95], v[144:147], v[198:201], v[92:95]
	v_mfma_f32_16x16x32_bf16 v[88:91], v[158:161], v[198:201], v[88:91]
	v_mfma_f32_16x16x32_bf16 v[76:79], v[144:147], v[206:209], v[76:79]
	v_mfma_f32_16x16x32_bf16 v[72:75], v[158:161], v[206:209], v[72:75]
	v_mfma_f32_16x16x32_bf16 v[124:127], v[154:157], v[186:189], v[124:127]
	v_mfma_f32_16x16x32_bf16 v[120:123], v[162:165], v[186:189], v[120:123]
	v_mfma_f32_16x16x32_bf16 v[108:111], v[154:157], v[194:197], v[108:111]
	v_mfma_f32_16x16x32_bf16 v[104:107], v[162:165], v[194:197], v[104:107]
	v_mfma_f32_16x16x32_bf16 v[92:95], v[154:157], v[202:205], v[92:95]
	v_mfma_f32_16x16x32_bf16 v[88:91], v[162:165], v[202:205], v[88:91]
	v_mfma_f32_16x16x32_bf16 v[76:79], v[154:157], v[210:213], v[76:79]
	v_mfma_f32_16x16x32_bf16 v[72:75], v[162:165], v[210:213], v[72:75]
	s_setprio 0
	s_setprio 1
	v_mfma_f32_16x16x32_bf16 v[116:119], v[166:169], v[182:185], v[116:119]
	v_mfma_f32_16x16x32_bf16 v[112:115], v[174:177], v[182:185], v[112:115]
	v_mfma_f32_16x16x32_bf16 v[100:103], v[166:169], v[190:193], v[100:103]
	v_mfma_f32_16x16x32_bf16 v[96:99], v[174:177], v[190:193], v[96:99]
	v_mfma_f32_16x16x32_bf16 v[84:87], v[166:169], v[198:201], v[84:87]
	v_mfma_f32_16x16x32_bf16 v[80:83], v[174:177], v[198:201], v[80:83]
	v_mfma_f32_16x16x32_bf16 v[68:71], v[166:169], v[206:209], v[68:71]
	v_mfma_f32_16x16x32_bf16 v[64:67], v[174:177], v[206:209], v[64:67]
	v_mfma_f32_16x16x32_bf16 v[116:119], v[170:173], v[186:189], v[116:119]
	v_mfma_f32_16x16x32_bf16 v[112:115], v[178:181], v[186:189], v[112:115]
	v_mfma_f32_16x16x32_bf16 v[100:103], v[170:173], v[194:197], v[100:103]
	v_mfma_f32_16x16x32_bf16 v[96:99], v[178:181], v[194:197], v[96:99]
	v_mfma_f32_16x16x32_bf16 v[84:87], v[170:173], v[202:205], v[84:87]
	v_mfma_f32_16x16x32_bf16 v[80:83], v[178:181], v[202:205], v[80:83]
	v_mfma_f32_16x16x32_bf16 v[68:71], v[170:173], v[210:213], v[68:71]
	v_mfma_f32_16x16x32_bf16 v[64:67], v[178:181], v[210:213], v[64:67]
	s_setprio 0
	s_barrier
	s_add_i32 s20, s48, s27
	v_lshl_add_u64 v[214:215], v[214:215], 0, s[10:11]
	s_mov_b32 m0, s20
	ds_read_b128 v[182:185], v153 offset:49152
	ds_read_b128 v[186:189], v153 offset:50176
	ds_read_b128 v[190:193], v153 offset:51200
	ds_read_b128 v[194:197], v153 offset:52224
	ds_read_b128 v[198:201], v153 offset:53248
	ds_read_b128 v[202:205], v153 offset:54272
	ds_read_b128 v[206:209], v153 offset:55296
	ds_read_b128 v[210:213], v153 offset:56320
	global_load_lds_dwordx4 v[214:215], off
	s_add_i32 m0, s20, 0x2000
	s_add_u32 s18, s18, 0xb0080
	v_lshl_add_u64 v[214:215], v[216:217], 0, s[10:11]
	s_addc_u32 s19, s19, 0
	s_add_i32 s20, s49, s27
	global_load_lds_dwordx4 v[214:215], off
	v_lshl_add_u64 v[214:215], s[18:19], 0, v[130:131]
	s_mov_b32 m0, s20
	s_nop 0
	global_load_lds_dwordx4 v[214:215], off
	v_lshl_add_u64 v[214:215], s[18:19], 0, v[134:135]
	s_add_i32 m0, s20, 0x2000
	s_nop 0
	global_load_lds_dwordx4 v[214:215], off
	v_lshl_add_u64 v[214:215], v[218:219], 0, s[10:11]
	s_mov_b32 m0, s36
	s_nop 0
	global_load_lds_dwordx4 v[214:215], off
	v_lshl_add_u64 v[214:215], v[220:221], 0, s[10:11]
	s_mov_b32 m0, s37
	s_nop 0
	global_load_lds_dwordx4 v[214:215], off
	s_waitcnt vmcnt(8)
	s_waitcnt lgkmcnt(0)
	s_barrier
	s_setprio 1
	s_waitcnt lgkmcnt(0)
	v_mfma_f32_16x16x32_bf16 v[60:63], v[144:147], v[182:185], v[60:63]
	v_mfma_f32_16x16x32_bf16 v[56:59], v[158:161], v[182:185], v[56:59]
	v_mfma_f32_16x16x32_bf16 v[44:47], v[144:147], v[190:193], v[44:47]
	v_mfma_f32_16x16x32_bf16 v[40:43], v[158:161], v[190:193], v[40:43]
	v_mfma_f32_16x16x32_bf16 v[28:31], v[144:147], v[198:201], v[28:31]
	v_mfma_f32_16x16x32_bf16 v[24:27], v[158:161], v[198:201], v[24:27]
	v_mfma_f32_16x16x32_bf16 v[12:15], v[144:147], v[206:209], v[12:15]
	v_mfma_f32_16x16x32_bf16 v[8:11], v[158:161], v[206:209], v[8:11]
	v_mfma_f32_16x16x32_bf16 v[60:63], v[154:157], v[186:189], v[60:63]
	v_mfma_f32_16x16x32_bf16 v[56:59], v[162:165], v[186:189], v[56:59]
	v_mfma_f32_16x16x32_bf16 v[44:47], v[154:157], v[194:197], v[44:47]
	v_mfma_f32_16x16x32_bf16 v[40:43], v[162:165], v[194:197], v[40:43]
	v_mfma_f32_16x16x32_bf16 v[28:31], v[154:157], v[202:205], v[28:31]
	v_mfma_f32_16x16x32_bf16 v[24:27], v[162:165], v[202:205], v[24:27]
	v_mfma_f32_16x16x32_bf16 v[12:15], v[154:157], v[210:213], v[12:15]
	v_mfma_f32_16x16x32_bf16 v[8:11], v[162:165], v[210:213], v[8:11]
	s_setprio 0
	s_setprio 1
	v_mfma_f32_16x16x32_bf16 v[52:55], v[166:169], v[182:185], v[52:55]
	v_mfma_f32_16x16x32_bf16 v[48:51], v[174:177], v[182:185], v[48:51]
	v_mfma_f32_16x16x32_bf16 v[36:39], v[166:169], v[190:193], v[36:39]
	v_mfma_f32_16x16x32_bf16 v[32:35], v[174:177], v[190:193], v[32:35]
	v_mfma_f32_16x16x32_bf16 v[20:23], v[166:169], v[198:201], v[20:23]
	v_mfma_f32_16x16x32_bf16 v[16:19], v[174:177], v[198:201], v[16:19]
	v_mfma_f32_16x16x32_bf16 v[4:7], v[166:169], v[206:209], v[4:7]
	v_mfma_f32_16x16x32_bf16 v[0:3], v[174:177], v[206:209], v[0:3]
	v_mfma_f32_16x16x32_bf16 v[52:55], v[170:173], v[186:189], v[52:55]
	v_mfma_f32_16x16x32_bf16 v[48:51], v[178:181], v[186:189], v[48:51]
	v_mfma_f32_16x16x32_bf16 v[36:39], v[170:173], v[194:197], v[36:39]
	v_mfma_f32_16x16x32_bf16 v[32:35], v[178:181], v[194:197], v[32:35]
	v_mfma_f32_16x16x32_bf16 v[20:23], v[170:173], v[202:205], v[20:23]
	v_mfma_f32_16x16x32_bf16 v[16:19], v[178:181], v[202:205], v[16:19]
	v_mfma_f32_16x16x32_bf16 v[4:7], v[170:173], v[210:213], v[4:7]
	v_mfma_f32_16x16x32_bf16 v[0:3], v[178:181], v[210:213], v[0:3]
	s_setprio 0
	s_barrier
	s_add_i32 s47, s47, 2
	s_add_u32 s16, s16, 0x100
	s_addc_u32 s17, s17, 0
	s_add_u32 s45, s45, 0x100
	s_addc_u32 s46, s46, 0
	s_cmp_gt_u32 s47, 41
	s_cbranch_scc0 .LBB0_1331
	s_and_b64 vcc, exec, s[12:13]
	s_cbranch_vccz .LBB0_1334
	s_barrier
